# speedup vs baseline: 1.0054x; 1.0054x over previous
; #define LDA(dst, b, h) for (int m = 0; m < 4; ++m) for (int k = 0; k < 2; ++k) \
;     dst[m][k] = *reinterpret_cast<const bf16x8*>((char*)SA(b, h) + lds_byte(wr * 64 + m * 16 + fr, k * 32 + fq * 8))
; #define LDB(dst, b, h) for (int n = 0; n < 2; ++n) for (int k = 0; k < 2; ++k) \
;     dst[n][k] = *reinterpret_cast<const bf16x8*>((char*)SB(b, h) + lds_byte(wc * 32 + n * 16 + fr, k * 32 + fq * 8))
; #define MMA(ai, bj, At, Bt_) do { __builtin_amdgcn_s_setprio(1); \
;     for (int m = 0; m < 4; ++m) for (int n = 0; n < 2; ++n) for (int k = 0; k < 2; ++k) \
;       acc[ai][bj][m][n] = __builtin_amdgcn_mfma_f32_16x16x32_bf16(At[m][k], Bt_[n][k], acc[ai][bj][m][n], 0, 0, 0); \
;     __builtin_amdgcn_s_setprio(0); } while (0)
; #define WAIT_L(n) asm volatile("s_waitcnt lgkmcnt(" #n ")" ::: "memory")
; #define BAR __builtin_amdgcn_s_barrier()
; #define SCHED __builtin_amdgcn_sched_barrier(0)
;     ...
;       LDB(B0, 0, 0); SCHED; LDA(At, 0, 0); STAGE(SA(1, 1), A, brow + HALF, t + 1);
;       WAIT_L(8); BAR; WAIT_L(0); MMA(0, 0, At, B0); BAR; SCHED;
;       LDB(B1, 0, 1); STAGE(SB(0, 0), Bt, bcol, t + 2);
;       BAR; WAIT_L(0); MMA(0, 1, At, B1); BAR;
;       LDA(At, 0, 1); STAGE(SA(0, 0), A, brow, t + 2);
;       BAR; WAIT_L(0); MMA(1, 0, At, B0); BAR; SCHED;
.LBB0_98:
	v_add_u32_e32 v143, s2, v142
	ds_read_b128 v[146:149], v143
	ds_read_b128 v[150:153], v143 offset:1024
	ds_read_b128 v[154:157], v143 offset:2048
	ds_read_b128 v[158:161], v143 offset:3072
	s_add_u32 s66, s55, s4
	s_addc_u32 s67, s57, s5
	s_add_i32 s63, s15, 0xc000
	ds_read_b128 v[162:165], v133
	ds_read_b128 v[184:187], v133 offset:1024
	ds_read_b128 v[188:191], v134
	ds_read_b128 v[192:195], v134 offset:1024
	ds_read_b128 v[196:199], v137
	ds_read_b128 v[200:203], v137 offset:1024
	ds_read_b128 v[204:207], v139
	ds_read_b128 v[208:211], v139 offset:1024
	s_mov_b32 m0, s63
	v_lshl_add_u64 v[144:145], s[66:67], 0, v[0:1]
	s_add_i32 s59, s15, 0xe000
	global_load_lds_dwordx4 v[144:145], off
	v_lshl_add_u64 v[144:145], s[66:67], 0, v[140:141]
	s_mov_b32 m0, s59
	s_nop 0
	global_load_lds_dwordx4 v[144:145], off
	s_waitcnt lgkmcnt(8)
	s_barrier
	s_waitcnt lgkmcnt(0)
	v_mfma_f32_16x16x32_bf16 v[126:129], v[162:165], v[146:149], v[126:129]
	v_mfma_f32_16x16x32_bf16 v[122:125], v[162:165], v[154:157], v[122:125]
	v_mfma_f32_16x16x32_bf16 v[118:121], v[188:191], v[146:149], v[118:121]
	v_mfma_f32_16x16x32_bf16 v[114:117], v[188:191], v[154:157], v[114:117]
	v_mfma_f32_16x16x32_bf16 v[110:113], v[196:199], v[146:149], v[110:113]
	v_mfma_f32_16x16x32_bf16 v[106:109], v[196:199], v[154:157], v[106:109]
	v_mfma_f32_16x16x32_bf16 v[102:105], v[204:207], v[146:149], v[102:105]
	v_mfma_f32_16x16x32_bf16 v[98:101], v[204:207], v[154:157], v[98:101]
	v_mfma_f32_16x16x32_bf16 v[126:129], v[184:187], v[150:153], v[126:129]
	v_mfma_f32_16x16x32_bf16 v[122:125], v[184:187], v[158:161], v[122:125]
	v_mfma_f32_16x16x32_bf16 v[118:121], v[192:195], v[150:153], v[118:121]
	v_mfma_f32_16x16x32_bf16 v[114:117], v[192:195], v[158:161], v[114:117]
	v_mfma_f32_16x16x32_bf16 v[110:113], v[200:203], v[150:153], v[110:113]
	v_mfma_f32_16x16x32_bf16 v[106:109], v[200:203], v[158:161], v[106:109]
	v_mfma_f32_16x16x32_bf16 v[102:105], v[208:211], v[150:153], v[102:105]
	v_mfma_f32_16x16x32_bf16 v[98:101], v[208:211], v[158:161], v[98:101]
	s_barrier
	s_add_i32 s58, s58, 2
	s_add_u32 s65, s50, s4
	s_addc_u32 s70, s51, s5
	s_add_u32 s66, s65, 0x100
	v_add_u32_e32 v144, s76, v142
	s_addc_u32 s67, s70, 0
	s_mov_b32 m0, s16
	ds_read_b128 v[212:215], v144
	ds_read_b128 v[216:219], v144 offset:1024
	ds_read_b128 v[220:223], v144 offset:2048
	ds_read_b128 v[224:227], v144 offset:3072
	s_nop 0
	v_lshl_add_u64 v[166:167], s[66:67], 0, v[0:1]
	global_load_lds_dwordx4 v[166:167], off
	v_lshl_add_u64 v[166:167], s[66:67], 0, v[140:141]
	s_mov_b32 m0, s17
	s_nop 0
	global_load_lds_dwordx4 v[166:167], off
	s_barrier
	s_waitcnt lgkmcnt(0)
	v_mfma_f32_16x16x32_bf16 v[94:97], v[162:165], v[212:215], v[94:97]
	v_mfma_f32_16x16x32_bf16 v[90:93], v[162:165], v[220:223], v[90:93]
	v_mfma_f32_16x16x32_bf16 v[86:89], v[188:191], v[212:215], v[86:89]
	v_mfma_f32_16x16x32_bf16 v[82:85], v[188:191], v[220:223], v[82:85]
	v_mfma_f32_16x16x32_bf16 v[78:81], v[196:199], v[212:215], v[78:81]
	v_mfma_f32_16x16x32_bf16 v[74:77], v[196:199], v[220:223], v[74:77]
	v_mfma_f32_16x16x32_bf16 v[70:73], v[204:207], v[212:215], v[70:73]
	v_mfma_f32_16x16x32_bf16 v[66:69], v[204:207], v[220:223], v[66:69]
	v_mfma_f32_16x16x32_bf16 v[94:97], v[184:187], v[216:219], v[94:97]
	v_mfma_f32_16x16x32_bf16 v[90:93], v[184:187], v[224:227], v[90:93]
	v_mfma_f32_16x16x32_bf16 v[86:89], v[192:195], v[216:219], v[86:89]
	v_mfma_f32_16x16x32_bf16 v[82:85], v[192:195], v[224:227], v[82:85]
	v_mfma_f32_16x16x32_bf16 v[78:81], v[200:203], v[216:219], v[78:81]
	v_mfma_f32_16x16x32_bf16 v[74:77], v[200:203], v[224:227], v[74:77]
	v_mfma_f32_16x16x32_bf16 v[70:73], v[208:211], v[216:219], v[70:73]
	v_mfma_f32_16x16x32_bf16 v[66:69], v[208:211], v[224:227], v[66:69]
	s_add_u32 s71, s44, s4
	s_addc_u32 s72, s45, s5
	s_add_u32 s66, s71, 0x100
	s_addc_u32 s67, s72, 0
	s_mov_b32 m0, s15
	s_barrier
	ds_read_b128 v[162:165], v133 offset:16384
	ds_read_b128 v[184:187], v133 offset:17408
	ds_read_b128 v[188:191], v134 offset:16384
	ds_read_b128 v[192:195], v134 offset:17408
	ds_read_b128 v[196:199], v137 offset:16384
	ds_read_b128 v[200:203], v137 offset:17408
	ds_read_b128 v[204:207], v139 offset:16384
	ds_read_b128 v[208:211], v139 offset:17408
	s_nop 0
	v_lshl_add_u64 v[166:167], s[66:67], 0, v[0:1]
	global_load_lds_dwordx4 v[166:167], off
	v_lshl_add_u64 v[166:167], s[66:67], 0, v[140:141]
	s_mov_b32 m0, s18
	s_nop 0
	global_load_lds_dwordx4 v[166:167], off
	s_barrier
	s_waitcnt lgkmcnt(0)
	v_mfma_f32_16x16x32_bf16 v[62:65], v[162:165], v[146:149], v[62:65]
	v_mfma_f32_16x16x32_bf16 v[58:61], v[162:165], v[154:157], v[58:61]
	v_mfma_f32_16x16x32_bf16 v[54:57], v[188:191], v[146:149], v[54:57]
	v_mfma_f32_16x16x32_bf16 v[50:53], v[188:191], v[154:157], v[50:53]
	v_mfma_f32_16x16x32_bf16 v[46:49], v[196:199], v[146:149], v[46:49]
	v_mfma_f32_16x16x32_bf16 v[42:45], v[196:199], v[154:157], v[42:45]
	v_mfma_f32_16x16x32_bf16 v[38:41], v[204:207], v[146:149], v[38:41]
	v_mfma_f32_16x16x32_bf16 v[34:37], v[204:207], v[154:157], v[34:37]
	v_mfma_f32_16x16x32_bf16 v[62:65], v[184:187], v[150:153], v[62:65]
	v_mfma_f32_16x16x32_bf16 v[58:61], v[184:187], v[158:161], v[58:61]
	v_mfma_f32_16x16x32_bf16 v[54:57], v[192:195], v[150:153], v[54:57]
	v_mfma_f32_16x16x32_bf16 v[50:53], v[192:195], v[158:161], v[50:53]
	v_mfma_f32_16x16x32_bf16 v[46:49], v[200:203], v[150:153], v[46:49]
	v_mfma_f32_16x16x32_bf16 v[42:45], v[200:203], v[158:161], v[42:45]
	v_mfma_f32_16x16x32_bf16 v[38:41], v[208:211], v[150:153], v[38:41]
	v_mfma_f32_16x16x32_bf16 v[34:37], v[208:211], v[158:161], v[34:37]
	s_barrier
; #define LDA(dst, b, h) for (int m = 0; m < 4; ++m) for (int k = 0; k < 2; ++k) \
;     dst[m][k] = *reinterpret_cast<const bf16x8*>((char*)SA(b, h) + lds_byte(wr * 64 + m * 16 + fr, k * 32 + fq * 8))
; #define LDB(dst, b, h) for (int n = 0; n < 2; ++n) for (int k = 0; k < 2; ++k) \
;     dst[n][k] = *reinterpret_cast<const bf16x8*>((char*)SB(b, h) + lds_byte(wc * 32 + n * 16 + fr, k * 32 + fq * 8))
; #define MMA(ai, bj, At, Bt_) do { __builtin_amdgcn_s_setprio(1); \
;     for (int m = 0; m < 4; ++m) for (int n = 0; n < 2; ++n) for (int k = 0; k < 2; ++k) \
;       acc[ai][bj][m][n] = __builtin_amdgcn_mfma_f32_16x16x32_bf16(At[m][k], Bt_[n][k], acc[ai][bj][m][n], 0, 0, 0); \
;     __builtin_amdgcn_s_setprio(0); } while (0)
; #define WAIT_V(n) asm volatile("s_waitcnt vmcnt(" #n ")" ::: "memory")
; #define WAIT_L(n) asm volatile("s_waitcnt lgkmcnt(" #n ")" ::: "memory")
; #define BAR __builtin_amdgcn_s_barrier()
; #define SCHED __builtin_amdgcn_sched_barrier(0)
;     ...
;       STAGE(SB(0, 1), Bt, bcol + HALF, t + 2);
;       WAIT_V(6); BAR; MMA(1, 1, At, B1); BAR;
;       LDB(B0, 1, 0); SCHED; LDA(At, 1, 0); STAGE(SA(0, 1), A, brow + HALF, t + 2);
;       WAIT_L(8); BAR; WAIT_L(0); MMA(0, 0, At, B0); BAR; SCHED;
;       LDB(B1, 1, 1); STAGE(SB(1, 0), Bt, bcol, t + 3);
;       BAR; WAIT_L(0); MMA(0, 1, At, B1); BAR;
;       LDA(At, 1, 1); STAGE(SA(1, 0), A, brow, t + 3);
	s_add_u32 s73, s6, s4
	s_addc_u32 s82, s7, s5
	s_add_u32 s66, s73, 0x160100
	s_addc_u32 s67, s82, 0
	s_mov_b32 m0, s19
	s_nop 0
	v_lshl_add_u64 v[146:147], s[66:67], 0, v[0:1]
	global_load_lds_dwordx4 v[146:147], off
	v_lshl_add_u64 v[146:147], s[66:67], 0, v[140:141]
	s_mov_b32 m0, s21
	s_nop 0
	global_load_lds_dwordx4 v[146:147], off
	s_waitcnt vmcnt(6)
	s_barrier
	v_mfma_f32_16x16x32_bf16 v[30:33], v[162:165], v[212:215], v[30:33]
	v_mfma_f32_16x16x32_bf16 v[26:29], v[162:165], v[220:223], v[26:29]
	v_mfma_f32_16x16x32_bf16 v[22:25], v[188:191], v[212:215], v[22:25]
	v_mfma_f32_16x16x32_bf16 v[18:21], v[188:191], v[220:223], v[18:21]
	v_mfma_f32_16x16x32_bf16 v[14:17], v[196:199], v[212:215], v[14:17]
	v_mfma_f32_16x16x32_bf16 v[10:13], v[196:199], v[220:223], v[10:13]
	v_mfma_f32_16x16x32_bf16 v[6:9], v[204:207], v[212:215], v[6:9]
	v_mfma_f32_16x16x32_bf16 v[2:5], v[204:207], v[220:223], v[2:5]
	v_mfma_f32_16x16x32_bf16 v[30:33], v[184:187], v[216:219], v[30:33]
	v_mfma_f32_16x16x32_bf16 v[26:29], v[184:187], v[224:227], v[26:29]
	v_mfma_f32_16x16x32_bf16 v[22:25], v[192:195], v[216:219], v[22:25]
	v_mfma_f32_16x16x32_bf16 v[18:21], v[192:195], v[224:227], v[18:21]
	v_mfma_f32_16x16x32_bf16 v[14:17], v[200:203], v[216:219], v[14:17]
	v_mfma_f32_16x16x32_bf16 v[10:13], v[200:203], v[224:227], v[10:13]
	v_mfma_f32_16x16x32_bf16 v[6:9], v[208:211], v[216:219], v[6:9]
	v_mfma_f32_16x16x32_bf16 v[2:5], v[208:211], v[224:227], v[2:5]
	v_add_u32_e32 v145, s77, v142
	s_barrier
	ds_read_b128 v[148:151], v145
	ds_read_b128 v[152:155], v145 offset:1024
	ds_read_b128 v[156:159], v145 offset:2048
	ds_read_b128 v[160:163], v145 offset:3072
	s_add_u32 s66, s71, 0x160100
	s_addc_u32 s67, s72, 0
	s_mov_b32 m0, s30
	ds_read_b128 v[164:167], v133 offset:32768
	ds_read_b128 v[184:187], v133 offset:33792
	ds_read_b128 v[188:191], v134 offset:32768
	ds_read_b128 v[192:195], v134 offset:33792
	ds_read_b128 v[196:199], v137 offset:32768
	ds_read_b128 v[200:203], v137 offset:33792
	ds_read_b128 v[204:207], v139 offset:32768
	ds_read_b128 v[208:211], v139 offset:33792
	s_nop 0
	v_lshl_add_u64 v[146:147], s[66:67], 0, v[0:1]
	global_load_lds_dwordx4 v[146:147], off
	v_lshl_add_u64 v[146:147], s[66:67], 0, v[140:141]
	s_mov_b32 m0, s31
	s_nop 0
	global_load_lds_dwordx4 v[146:147], off
	s_waitcnt lgkmcnt(8)
	s_barrier
	s_waitcnt lgkmcnt(0)
	v_mfma_f32_16x16x32_bf16 v[126:129], v[164:167], v[148:151], v[126:129]
	v_mfma_f32_16x16x32_bf16 v[122:125], v[164:167], v[156:159], v[122:125]
	v_mfma_f32_16x16x32_bf16 v[118:121], v[188:191], v[148:151], v[118:121]
	v_mfma_f32_16x16x32_bf16 v[114:117], v[188:191], v[156:159], v[114:117]
	v_mfma_f32_16x16x32_bf16 v[110:113], v[196:199], v[148:151], v[110:113]
	v_mfma_f32_16x16x32_bf16 v[106:109], v[196:199], v[156:159], v[106:109]
	v_mfma_f32_16x16x32_bf16 v[102:105], v[204:207], v[148:151], v[102:105]
	v_mfma_f32_16x16x32_bf16 v[98:101], v[204:207], v[156:159], v[98:101]
	v_mfma_f32_16x16x32_bf16 v[126:129], v[184:187], v[152:155], v[126:129]
	v_mfma_f32_16x16x32_bf16 v[122:125], v[184:187], v[160:163], v[122:125]
	v_mfma_f32_16x16x32_bf16 v[118:121], v[192:195], v[152:155], v[118:121]
	v_mfma_f32_16x16x32_bf16 v[114:117], v[192:195], v[160:163], v[114:117]
	v_mfma_f32_16x16x32_bf16 v[110:113], v[200:203], v[152:155], v[110:113]
	v_mfma_f32_16x16x32_bf16 v[106:109], v[200:203], v[160:163], v[106:109]
	v_mfma_f32_16x16x32_bf16 v[102:105], v[208:211], v[152:155], v[102:105]
	v_mfma_f32_16x16x32_bf16 v[98:101], v[208:211], v[160:163], v[98:101]
	s_barrier
	s_add_u32 s66, s65, 0x180
	v_add_u32_e32 v146, s78, v142
	s_addc_u32 s67, s70, 0
	s_mov_b32 m0, s34
	ds_read_b128 v[212:215], v146
	ds_read_b128 v[216:219], v146 offset:1024
	ds_read_b128 v[220:223], v146 offset:2048
	ds_read_b128 v[224:227], v146 offset:3072
	s_nop 0
	v_lshl_add_u64 v[228:229], s[66:67], 0, v[0:1]
	global_load_lds_dwordx4 v[228:229], off
	v_lshl_add_u64 v[228:229], s[66:67], 0, v[140:141]
	s_mov_b32 m0, s35
	s_nop 0
	global_load_lds_dwordx4 v[228:229], off
	s_barrier
	s_waitcnt lgkmcnt(0)
	v_mfma_f32_16x16x32_bf16 v[94:97], v[164:167], v[212:215], v[94:97]
	v_mfma_f32_16x16x32_bf16 v[90:93], v[164:167], v[220:223], v[90:93]
	v_mfma_f32_16x16x32_bf16 v[86:89], v[188:191], v[212:215], v[86:89]
	v_mfma_f32_16x16x32_bf16 v[82:85], v[188:191], v[220:223], v[82:85]
	v_mfma_f32_16x16x32_bf16 v[78:81], v[196:199], v[212:215], v[78:81]
	v_mfma_f32_16x16x32_bf16 v[74:77], v[196:199], v[220:223], v[74:77]
	v_mfma_f32_16x16x32_bf16 v[70:73], v[204:207], v[212:215], v[70:73]
	v_mfma_f32_16x16x32_bf16 v[66:69], v[204:207], v[220:223], v[66:69]
	v_mfma_f32_16x16x32_bf16 v[94:97], v[184:187], v[216:219], v[94:97]
	v_mfma_f32_16x16x32_bf16 v[90:93], v[184:187], v[224:227], v[90:93]
	v_mfma_f32_16x16x32_bf16 v[86:89], v[192:195], v[216:219], v[86:89]
	v_mfma_f32_16x16x32_bf16 v[82:85], v[192:195], v[224:227], v[82:85]
	v_mfma_f32_16x16x32_bf16 v[78:81], v[200:203], v[216:219], v[78:81]
	v_mfma_f32_16x16x32_bf16 v[74:77], v[200:203], v[224:227], v[74:77]
	v_mfma_f32_16x16x32_bf16 v[70:73], v[208:211], v[216:219], v[70:73]
	v_mfma_f32_16x16x32_bf16 v[66:69], v[208:211], v[224:227], v[66:69]
	s_add_u32 s66, s71, 0x180
	s_addc_u32 s67, s72, 0
	s_mov_b32 m0, s37
	s_barrier
	ds_read_b128 v[164:167], v133 offset:49152
	ds_read_b128 v[184:187], v133 offset:50176
	ds_read_b128 v[188:191], v134 offset:49152
	ds_read_b128 v[192:195], v134 offset:50176
	ds_read_b128 v[196:199], v137 offset:49152
	ds_read_b128 v[200:203], v137 offset:50176
	ds_read_b128 v[204:207], v139 offset:49152
	ds_read_b128 v[208:211], v139 offset:50176
	s_nop 0
	v_lshl_add_u64 v[228:229], s[66:67], 0, v[0:1]
	global_load_lds_dwordx4 v[228:229], off
	v_lshl_add_u64 v[228:229], s[66:67], 0, v[140:141]
	s_mov_b32 m0, s38
	s_nop 0
	global_load_lds_dwordx4 v[228:229], off
	s_barrier
; #define LDA(dst, b, h) for (int m = 0; m < 4; ++m) for (int k = 0; k < 2; ++k) \
;     dst[m][k] = *reinterpret_cast<const bf16x8*>((char*)SA(b, h) + lds_byte(wr * 64 + m * 16 + fr, k * 32 + fq * 8))
; #define LDB(dst, b, h) for (int n = 0; n < 2; ++n) for (int k = 0; k < 2; ++k) \
;     dst[n][k] = *reinterpret_cast<const bf16x8*>((char*)SB(b, h) + lds_byte(wc * 32 + n * 16 + fr, k * 32 + fq * 8))
; #define MMA(ai, bj, At, Bt_) do { __builtin_amdgcn_s_setprio(1); \
;     for (int m = 0; m < 4; ++m) for (int n = 0; n < 2; ++n) for (int k = 0; k < 2; ++k) \
;       acc[ai][bj][m][n] = __builtin_amdgcn_mfma_f32_16x16x32_bf16(At[m][k], Bt_[n][k], acc[ai][bj][m][n], 0, 0, 0); \
;     __builtin_amdgcn_s_setprio(0); } while (0)
; #define WAIT_V(n) asm volatile("s_waitcnt vmcnt(" #n ")" ::: "memory")
; #define WAIT_L(n) asm volatile("s_waitcnt lgkmcnt(" #n ")" ::: "memory")
; #define BAR __builtin_amdgcn_s_barrier()
; #define SCHED __builtin_amdgcn_sched_barrier(0)
;     ...
;       BAR; WAIT_L(0); MMA(1, 0, At, B0); BAR; SCHED;
;       STAGE(SB(1, 1), Bt, bcol + HALF, t + 3);
;       WAIT_V(6); BAR; MMA(1, 1, At, B1); BAR;
;     }
;     { LDB(B0, 0, 0); LDA(At, 0, 0); STAGE(SA(1, 1), A, brow + HALF, nt - 1);
;       BAR; WAIT_L(0); MMA(0, 0, At, B0); BAR;
;       LDB(B1, 0, 1); BAR; WAIT_L(0); MMA(0, 1, At, B1); BAR;
	s_waitcnt lgkmcnt(0)
	v_mfma_f32_16x16x32_bf16 v[62:65], v[164:167], v[148:151], v[62:65]
	v_mfma_f32_16x16x32_bf16 v[58:61], v[164:167], v[156:159], v[58:61]
	v_mfma_f32_16x16x32_bf16 v[54:57], v[188:191], v[148:151], v[54:57]
	v_mfma_f32_16x16x32_bf16 v[50:53], v[188:191], v[156:159], v[50:53]
	v_mfma_f32_16x16x32_bf16 v[46:49], v[196:199], v[148:151], v[46:49]
	v_mfma_f32_16x16x32_bf16 v[42:45], v[196:199], v[156:159], v[42:45]
	v_mfma_f32_16x16x32_bf16 v[38:41], v[204:207], v[148:151], v[38:41]
	v_mfma_f32_16x16x32_bf16 v[34:37], v[204:207], v[156:159], v[34:37]
	v_mfma_f32_16x16x32_bf16 v[62:65], v[184:187], v[152:155], v[62:65]
	v_mfma_f32_16x16x32_bf16 v[58:61], v[184:187], v[160:163], v[58:61]
	v_mfma_f32_16x16x32_bf16 v[54:57], v[192:195], v[152:155], v[54:57]
	v_mfma_f32_16x16x32_bf16 v[50:53], v[192:195], v[160:163], v[50:53]
	v_mfma_f32_16x16x32_bf16 v[46:49], v[200:203], v[152:155], v[46:49]
	v_mfma_f32_16x16x32_bf16 v[42:45], v[200:203], v[160:163], v[42:45]
	v_mfma_f32_16x16x32_bf16 v[38:41], v[208:211], v[152:155], v[38:41]
	v_mfma_f32_16x16x32_bf16 v[34:37], v[208:211], v[160:163], v[34:37]
	s_barrier
	s_add_u32 s66, s73, 0x160180
	s_addc_u32 s67, s82, 0
	s_mov_b32 m0, s41
	s_nop 0
	v_lshl_add_u64 v[148:149], s[66:67], 0, v[0:1]
	global_load_lds_dwordx4 v[148:149], off
	v_lshl_add_u64 v[148:149], s[66:67], 0, v[140:141]
	s_mov_b32 m0, s42
	s_nop 0
	global_load_lds_dwordx4 v[148:149], off
	s_waitcnt vmcnt(6)
	s_barrier
	v_mfma_f32_16x16x32_bf16 v[30:33], v[164:167], v[212:215], v[30:33]
	v_mfma_f32_16x16x32_bf16 v[26:29], v[164:167], v[220:223], v[26:29]
	v_mfma_f32_16x16x32_bf16 v[22:25], v[188:191], v[212:215], v[22:25]
	v_mfma_f32_16x16x32_bf16 v[18:21], v[188:191], v[220:223], v[18:21]
	v_mfma_f32_16x16x32_bf16 v[14:17], v[196:199], v[212:215], v[14:17]
	v_mfma_f32_16x16x32_bf16 v[10:13], v[196:199], v[220:223], v[10:13]
	v_mfma_f32_16x16x32_bf16 v[6:9], v[204:207], v[212:215], v[6:9]
	v_mfma_f32_16x16x32_bf16 v[2:5], v[204:207], v[220:223], v[2:5]
	v_mfma_f32_16x16x32_bf16 v[30:33], v[184:187], v[216:219], v[30:33]
	v_mfma_f32_16x16x32_bf16 v[26:29], v[184:187], v[224:227], v[26:29]
	v_mfma_f32_16x16x32_bf16 v[22:25], v[192:195], v[216:219], v[22:25]
	v_mfma_f32_16x16x32_bf16 v[18:21], v[192:195], v[224:227], v[18:21]
	v_mfma_f32_16x16x32_bf16 v[14:17], v[200:203], v[216:219], v[14:17]
	v_mfma_f32_16x16x32_bf16 v[10:13], v[200:203], v[224:227], v[10:13]
	v_mfma_f32_16x16x32_bf16 v[6:9], v[208:211], v[216:219], v[6:9]
	v_mfma_f32_16x16x32_bf16 v[2:5], v[208:211], v[224:227], v[2:5]
	s_add_u32 s6, s6, 0x100
	s_addc_u32 s7, s7, 0
	s_add_u32 s44, s44, 0x100
	s_addc_u32 s45, s45, 0
	s_add_u32 s50, s50, 0x100
	s_addc_u32 s51, s51, 0
	s_add_u32 s55, s55, 0x100
	s_addc_u32 s57, s57, 0
	s_cmp_ge_u32 s58, s43
	s_barrier
	s_cbranch_scc0 .LBB0_98
	s_add_i32 s4, s48, s14
	s_add_i32 s48, s4, -1
	s_lshl_b64 s[4:5], s[48:49], 7
	s_add_u32 s4, s22, s4
	s_addc_u32 s5, s23, s5
	s_add_u32 s4, s4, s40
	s_addc_u32 s5, s5, s39
	s_mov_b32 m0, s63
	ds_read_b128 v[148:151], v143
	ds_read_b128 v[152:155], v143 offset:1024
	ds_read_b128 v[156:159], v143 offset:2048
	ds_read_b128 v[160:163], v143 offset:3072
	ds_read_b128 v[164:167], v133
	ds_read_b128 v[184:187], v133 offset:1024
	ds_read_b128 v[188:191], v134
	ds_read_b128 v[192:195], v134 offset:1024
	ds_read_b128 v[196:199], v137
	ds_read_b128 v[200:203], v137 offset:1024
	ds_read_b128 v[204:207], v139
	ds_read_b128 v[208:211], v139 offset:1024
	s_nop 0
	v_lshl_add_u64 v[142:143], s[4:5], 0, v[0:1]
	global_load_lds_dwordx4 v[142:143], off
	v_lshl_add_u64 v[140:141], s[4:5], 0, v[140:141]
	s_mov_b32 m0, s59
	s_nop 0
	global_load_lds_dwordx4 v[140:141], off
	s_barrier
	s_waitcnt lgkmcnt(0)
	s_setprio 1
	s_waitcnt lgkmcnt(0)
	v_mfma_f32_16x16x32_bf16 v[126:129], v[164:167], v[148:151], v[126:129]
	v_mfma_f32_16x16x32_bf16 v[122:125], v[164:167], v[156:159], v[122:125]
	v_mfma_f32_16x16x32_bf16 v[118:121], v[188:191], v[148:151], v[118:121]
	v_mfma_f32_16x16x32_bf16 v[110:113], v[196:199], v[148:151], v[110:113]
	v_mfma_f32_16x16x32_bf16 v[106:109], v[196:199], v[156:159], v[106:109]
	v_mfma_f32_16x16x32_bf16 v[102:105], v[204:207], v[148:151], v[102:105]
	v_mfma_f32_16x16x32_bf16 v[98:101], v[204:207], v[156:159], v[98:101]
	v_mfma_f32_16x16x32_bf16 v[126:129], v[184:187], v[152:155], v[126:129]
	v_mfma_f32_16x16x32_bf16 v[122:125], v[184:187], v[160:163], v[122:125]
	v_mfma_f32_16x16x32_bf16 v[118:121], v[192:195], v[152:155], v[118:121]
	v_mfma_f32_16x16x32_bf16 v[114:117], v[188:191], v[156:159], v[114:117]
	v_mfma_f32_16x16x32_bf16 v[110:113], v[200:203], v[152:155], v[110:113]
	v_mfma_f32_16x16x32_bf16 v[106:109], v[200:203], v[160:163], v[106:109]
	v_mfma_f32_16x16x32_bf16 v[102:105], v[208:211], v[152:155], v[102:105]
	v_mfma_f32_16x16x32_bf16 v[98:101], v[208:211], v[160:163], v[98:101]
	v_mfma_f32_16x16x32_bf16 v[140:143], v[192:195], v[160:163], v[114:117]
	s_setprio 0
	s_barrier
	s_nop 0
	ds_read_b128 v[114:117], v144
	ds_read_b128 v[212:215], v144 offset:1024
	ds_read_b128 v[216:219], v144 offset:2048
	ds_read_b128 v[220:223], v144 offset:3072
	s_barrier
; #define LDA(dst, b, h) for (int m = 0; m < 4; ++m) for (int k = 0; k < 2; ++k) \
;     dst[m][k] = *reinterpret_cast<const bf16x8*>((char*)SA(b, h) + lds_byte(wr * 64 + m * 16 + fr, k * 32 + fq * 8))
; #define LDB(dst, b, h) for (int n = 0; n < 2; ++n) for (int k = 0; k < 2; ++k) \
;     dst[n][k] = *reinterpret_cast<const bf16x8*>((char*)SB(b, h) + lds_byte(wc * 32 + n * 16 + fr, k * 32 + fq * 8))
; #define MMA(ai, bj, At, Bt_) do { __builtin_amdgcn_s_setprio(1); \
;     for (int m = 0; m < 4; ++m) for (int n = 0; n < 2; ++n) for (int k = 0; k < 2; ++k) \
;       acc[ai][bj][m][n] = __builtin_amdgcn_mfma_f32_16x16x32_bf16(At[m][k], Bt_[n][k], acc[ai][bj][m][n], 0, 0, 0); \
;     __builtin_amdgcn_s_setprio(0); } while (0)
; #define WAIT_V(n) asm volatile("s_waitcnt vmcnt(" #n ")" ::: "memory")
; #define WAIT_L(n) asm volatile("s_waitcnt lgkmcnt(" #n ")" ::: "memory")
; #define BAR __builtin_amdgcn_s_barrier()
;     ...
;       LDB(B1, 0, 1); BAR; WAIT_L(0); MMA(0, 1, At, B1); BAR;
;       LDA(At, 0, 1); WAIT_V(4); BAR; WAIT_L(0); MMA(1, 0, At, B0); MMA(1, 1, At, B1); BAR; }
;     { LDB(B0, 1, 0); LDA(At, 1, 0); WAIT_V(2); BAR; WAIT_L(0); MMA(0, 0, At, B0); BAR;
	s_waitcnt lgkmcnt(0)
	s_setprio 1
	s_waitcnt lgkmcnt(0)
	v_mfma_f32_16x16x32_bf16 v[90:93], v[164:167], v[216:219], v[90:93]
	v_mfma_f32_16x16x32_bf16 v[86:89], v[188:191], v[114:117], v[86:89]
	v_mfma_f32_16x16x32_bf16 v[94:97], v[164:167], v[114:117], v[94:97]
	v_mfma_f32_16x16x32_bf16 v[90:93], v[184:187], v[220:223], v[90:93]
	v_mfma_f32_16x16x32_bf16 v[86:89], v[192:195], v[212:215], v[86:89]
	v_mfma_f32_16x16x32_bf16 v[82:85], v[188:191], v[216:219], v[82:85]
	v_mfma_f32_16x16x32_bf16 v[78:81], v[196:199], v[114:117], v[78:81]
	v_mfma_f32_16x16x32_bf16 v[74:77], v[196:199], v[216:219], v[74:77]
	v_mfma_f32_16x16x32_bf16 v[70:73], v[204:207], v[114:117], v[70:73]
	v_mfma_f32_16x16x32_bf16 v[66:69], v[204:207], v[216:219], v[66:69]
	v_mfma_f32_16x16x32_bf16 v[224:227], v[184:187], v[212:215], v[94:97]
	v_mfma_f32_16x16x32_bf16 v[164:167], v[192:195], v[220:223], v[82:85]
	v_mfma_f32_16x16x32_bf16 v[184:187], v[200:203], v[212:215], v[78:81]
	v_mfma_f32_16x16x32_bf16 v[188:191], v[200:203], v[220:223], v[74:77]
	v_mfma_f32_16x16x32_bf16 v[192:195], v[208:211], v[212:215], v[70:73]
	v_mfma_f32_16x16x32_bf16 v[196:199], v[208:211], v[220:223], v[66:69]
	s_setprio 0
	s_barrier
	s_nop 0
	ds_read_b128 v[66:69], v133 offset:16384
	ds_read_b128 v[70:73], v133 offset:17408
	ds_read_b128 v[74:77], v134 offset:16384
	ds_read_b128 v[78:81], v134 offset:17408
	ds_read_b128 v[82:85], v137 offset:16384
	ds_read_b128 v[94:97], v137 offset:17408
	ds_read_b128 v[200:203], v139 offset:16384
	ds_read_b128 v[204:207], v139 offset:17408
	s_waitcnt vmcnt(4)
	s_barrier
	s_waitcnt lgkmcnt(0)
	s_setprio 1
	s_waitcnt lgkmcnt(0)
	v_mfma_f32_16x16x32_bf16 v[62:65], v[66:69], v[148:151], v[62:65]
	v_mfma_f32_16x16x32_bf16 v[58:61], v[66:69], v[156:159], v[58:61]
	v_mfma_f32_16x16x32_bf16 v[54:57], v[74:77], v[148:151], v[54:57]
	v_mfma_f32_16x16x32_bf16 v[50:53], v[74:77], v[156:159], v[50:53]
	v_mfma_f32_16x16x32_bf16 v[46:49], v[82:85], v[148:151], v[46:49]
	v_mfma_f32_16x16x32_bf16 v[42:45], v[82:85], v[156:159], v[42:45]
	v_mfma_f32_16x16x32_bf16 v[38:41], v[200:203], v[148:151], v[38:41]
	v_mfma_f32_16x16x32_bf16 v[34:37], v[200:203], v[156:159], v[34:37]
	v_mfma_f32_16x16x32_bf16 v[62:65], v[70:73], v[152:155], v[62:65]
	v_mfma_f32_16x16x32_bf16 v[58:61], v[70:73], v[160:163], v[58:61]
	v_mfma_f32_16x16x32_bf16 v[54:57], v[78:81], v[152:155], v[54:57]
	v_mfma_f32_16x16x32_bf16 v[50:53], v[78:81], v[160:163], v[50:53]
	v_mfma_f32_16x16x32_bf16 v[46:49], v[94:97], v[152:155], v[46:49]
	v_mfma_f32_16x16x32_bf16 v[42:45], v[94:97], v[160:163], v[42:45]
	v_mfma_f32_16x16x32_bf16 v[38:41], v[204:207], v[152:155], v[38:41]
	v_mfma_f32_16x16x32_bf16 v[34:37], v[204:207], v[160:163], v[34:37]
	s_setprio 0
	s_setprio 1
	v_mfma_f32_16x16x32_bf16 v[30:33], v[66:69], v[114:117], v[30:33]
	v_mfma_f32_16x16x32_bf16 v[26:29], v[66:69], v[216:219], v[26:29]
	v_mfma_f32_16x16x32_bf16 v[22:25], v[74:77], v[114:117], v[22:25]
	v_mfma_f32_16x16x32_bf16 v[18:21], v[74:77], v[216:219], v[18:21]
	v_mfma_f32_16x16x32_bf16 v[14:17], v[82:85], v[114:117], v[14:17]
	v_mfma_f32_16x16x32_bf16 v[10:13], v[82:85], v[216:219], v[10:13]
	v_mfma_f32_16x16x32_bf16 v[6:9], v[200:203], v[114:117], v[6:9]
	v_mfma_f32_16x16x32_bf16 v[2:5], v[200:203], v[216:219], v[2:5]
	v_mfma_f32_16x16x32_bf16 v[148:151], v[70:73], v[212:215], v[30:33]
	v_mfma_f32_16x16x32_bf16 v[152:155], v[70:73], v[220:223], v[26:29]
	v_mfma_f32_16x16x32_bf16 v[156:159], v[78:81], v[212:215], v[22:25]
	v_mfma_f32_16x16x32_bf16 v[160:163], v[78:81], v[220:223], v[18:21]
	v_mfma_f32_16x16x32_bf16 v[208:211], v[94:97], v[212:215], v[14:17]
	v_mfma_f32_16x16x32_bf16 v[228:231], v[94:97], v[220:223], v[10:13]
	v_mfma_f32_16x16x32_bf16 v[212:215], v[204:207], v[212:215], v[6:9]
	v_mfma_f32_16x16x32_bf16 v[200:203], v[204:207], v[220:223], v[2:5]
	s_setprio 0
	s_barrier
	ds_read_b128 v[14:17], v145
	ds_read_b128 v[30:33], v145 offset:1024
	ds_read_b128 v[204:207], v145 offset:2048
	ds_read_b128 v[216:219], v145 offset:3072
	ds_read_b128 v[2:5], v133 offset:32768
	ds_read_b128 v[6:9], v133 offset:33792
	ds_read_b128 v[10:13], v134 offset:32768
	ds_read_b128 v[18:21], v134 offset:33792
	ds_read_b128 v[22:25], v137 offset:32768
	ds_read_b128 v[26:29], v137 offset:33792
	ds_read_b128 v[220:223], v139 offset:32768
	ds_read_b128 v[232:235], v139 offset:33792
	s_waitcnt vmcnt(2)
	s_barrier
; #define LDA(dst, b, h) for (int m = 0; m < 4; ++m) for (int k = 0; k < 2; ++k) \
;     dst[m][k] = *reinterpret_cast<const bf16x8*>((char*)SA(b, h) + lds_byte(wr * 64 + m * 16 + fr, k * 32 + fq * 8))
; #define LDB(dst, b, h) for (int n = 0; n < 2; ++n) for (int k = 0; k < 2; ++k) \
;     dst[n][k] = *reinterpret_cast<const bf16x8*>((char*)SB(b, h) + lds_byte(wc * 32 + n * 16 + fr, k * 32 + fq * 8))
; #define MMA(ai, bj, At, Bt_) do { __builtin_amdgcn_s_setprio(1); \
;     for (int m = 0; m < 4; ++m) for (int n = 0; n < 2; ++n) for (int k = 0; k < 2; ++k) \
;       acc[ai][bj][m][n] = __builtin_amdgcn_mfma_f32_16x16x32_bf16(At[m][k], Bt_[n][k], acc[ai][bj][m][n], 0, 0, 0); \
;     __builtin_amdgcn_s_setprio(0); } while (0)
; #define WAIT_V(n) asm volatile("s_waitcnt vmcnt(" #n ")" ::: "memory")
; #define WAIT_L(n) asm volatile("s_waitcnt lgkmcnt(" #n ")" ::: "memory")
; #define BAR __builtin_amdgcn_s_barrier()
;     ...
;     { LDB(B0, 1, 0); LDA(At, 1, 0); WAIT_V(2); BAR; WAIT_L(0); MMA(0, 0, At, B0); BAR;
;       LDB(B1, 1, 1); WAIT_V(0); BAR; WAIT_L(0); MMA(0, 1, At, B1); BAR;
;       LDA(At, 1, 1); BAR; WAIT_L(0); MMA(1, 0, At, B0); MMA(1, 1, At, B1); BAR; }
;     if (wr == 0) BAR;
	s_waitcnt lgkmcnt(0)
	s_setprio 1
	s_waitcnt lgkmcnt(0)
	v_mfma_f32_16x16x32_bf16 v[66:69], v[2:5], v[14:17], v[126:129]
	v_mfma_f32_16x16x32_bf16 v[114:117], v[6:9], v[30:33], v[66:69]
	v_mfma_f32_16x16x32_bf16 v[66:69], v[2:5], v[204:207], v[122:125]
	v_mfma_f32_16x16x32_bf16 v[126:129], v[6:9], v[216:219], v[66:69]
	v_mfma_f32_16x16x32_bf16 v[66:69], v[10:13], v[14:17], v[118:121]
	v_mfma_f32_16x16x32_bf16 v[82:85], v[18:21], v[30:33], v[66:69]
	v_mfma_f32_16x16x32_bf16 v[66:69], v[10:13], v[204:207], v[140:143]
	v_mfma_f32_16x16x32_bf16 v[94:97], v[18:21], v[216:219], v[66:69]
	v_mfma_f32_16x16x32_bf16 v[66:69], v[22:25], v[14:17], v[110:113]
	v_mfma_f32_16x16x32_bf16 v[74:77], v[26:29], v[30:33], v[66:69]
	v_mfma_f32_16x16x32_bf16 v[66:69], v[22:25], v[204:207], v[106:109]
	v_mfma_f32_16x16x32_bf16 v[78:81], v[26:29], v[216:219], v[66:69]
	v_mfma_f32_16x16x32_bf16 v[66:69], v[220:223], v[14:17], v[102:105]
	v_mfma_f32_16x16x32_bf16 v[70:73], v[220:223], v[204:207], v[98:101]
	v_mfma_f32_16x16x32_bf16 v[66:69], v[232:235], v[30:33], v[66:69]
	v_mfma_f32_16x16x32_bf16 v[70:73], v[232:235], v[216:219], v[70:73]
	s_setprio 0
	s_barrier
	ds_read_b128 v[140:143], v146
	ds_read_b128 v[236:239], v146 offset:1024
	ds_read_b128 v[240:243], v146 offset:2048
	ds_read_b128 v[144:147], v146 offset:3072
	s_waitcnt vmcnt(0)
	s_barrier
	s_waitcnt lgkmcnt(0)
	s_setprio 1
	s_waitcnt lgkmcnt(0)
	v_mfma_f32_16x16x32_bf16 v[98:101], v[2:5], v[140:143], v[224:227]
	v_mfma_f32_16x16x32_bf16 v[2:5], v[2:5], v[240:243], v[90:93]
	v_mfma_f32_16x16x32_bf16 v[118:121], v[6:9], v[144:147], v[2:5]
	v_mfma_f32_16x16x32_bf16 v[2:5], v[10:13], v[140:143], v[86:89]
	v_mfma_f32_16x16x32_bf16 v[102:105], v[18:21], v[236:239], v[2:5]
	v_mfma_f32_16x16x32_bf16 v[2:5], v[10:13], v[240:243], v[164:167]
	v_mfma_f32_16x16x32_bf16 v[122:125], v[18:21], v[144:147], v[2:5]
	v_mfma_f32_16x16x32_bf16 v[2:5], v[22:25], v[140:143], v[184:187]
	v_mfma_f32_16x16x32_bf16 v[90:93], v[26:29], v[236:239], v[2:5]
	v_mfma_f32_16x16x32_bf16 v[2:5], v[22:25], v[240:243], v[188:191]
	v_mfma_f32_16x16x32_bf16 v[110:113], v[26:29], v[144:147], v[2:5]
	v_mfma_f32_16x16x32_bf16 v[2:5], v[220:223], v[140:143], v[192:195]
	v_mfma_f32_16x16x32_bf16 v[86:89], v[232:235], v[236:239], v[2:5]
	v_mfma_f32_16x16x32_bf16 v[2:5], v[220:223], v[240:243], v[196:199]
	v_mfma_f32_16x16x32_bf16 v[98:101], v[6:9], v[236:239], v[98:101]
	v_mfma_f32_16x16x32_bf16 v[106:109], v[232:235], v[144:147], v[2:5]
	s_setprio 0
	s_barrier
	ds_read_b128 v[164:167], v133 offset:49152
	ds_read_b128 v[184:187], v133 offset:50176
	ds_read_b128 v[188:191], v134 offset:49152
	ds_read_b128 v[192:195], v134 offset:50176
	ds_read_b128 v[196:199], v137 offset:49152
	ds_read_b128 v[220:223], v137 offset:50176
	ds_read_b128 v[224:227], v139 offset:49152
	ds_read_b128 v[232:235], v139 offset:50176
	s_barrier
	s_waitcnt lgkmcnt(0)
	s_setprio 1
	s_waitcnt lgkmcnt(0)
	v_mfma_f32_16x16x32_bf16 v[6:9], v[164:167], v[204:207], v[58:61]
	v_mfma_f32_16x16x32_bf16 v[10:13], v[188:191], v[204:207], v[50:53]
	v_mfma_f32_16x16x32_bf16 v[2:5], v[164:167], v[14:17], v[62:65]
	v_mfma_f32_16x16x32_bf16 v[18:21], v[184:187], v[216:219], v[6:9]
	v_mfma_f32_16x16x32_bf16 v[6:9], v[188:191], v[14:17], v[54:57]
	v_mfma_f32_16x16x32_bf16 v[22:25], v[192:195], v[216:219], v[10:13]
	v_mfma_f32_16x16x32_bf16 v[10:13], v[196:199], v[14:17], v[46:49]
	v_mfma_f32_16x16x32_bf16 v[14:17], v[224:227], v[14:17], v[38:41]
	v_mfma_f32_16x16x32_bf16 v[2:5], v[184:187], v[30:33], v[2:5]
	v_mfma_f32_16x16x32_bf16 v[6:9], v[192:195], v[30:33], v[6:9]
	v_mfma_f32_16x16x32_bf16 v[10:13], v[220:223], v[30:33], v[10:13]
	v_mfma_f32_16x16x32_bf16 v[26:29], v[196:199], v[204:207], v[42:45]
	v_mfma_f32_16x16x32_bf16 v[14:17], v[232:235], v[30:33], v[14:17]
	v_mfma_f32_16x16x32_bf16 v[30:33], v[224:227], v[204:207], v[34:37]
	v_mfma_f32_16x16x32_bf16 v[26:29], v[220:223], v[216:219], v[26:29]
	v_mfma_f32_16x16x32_bf16 v[30:33], v[232:235], v[216:219], v[30:33]
	s_setprio 0
	s_setprio 1
	v_mfma_f32_16x16x32_bf16 v[38:41], v[164:167], v[240:243], v[152:155]
	v_mfma_f32_16x16x32_bf16 v[42:45], v[188:191], v[240:243], v[160:163]
	v_mfma_f32_16x16x32_bf16 v[46:49], v[196:199], v[240:243], v[228:231]
	v_mfma_f32_16x16x32_bf16 v[34:37], v[164:167], v[140:143], v[148:151]
	v_mfma_f32_16x16x32_bf16 v[50:53], v[184:187], v[144:147], v[38:41]
	v_mfma_f32_16x16x32_bf16 v[38:41], v[188:191], v[140:143], v[156:159]
	v_mfma_f32_16x16x32_bf16 v[54:57], v[192:195], v[144:147], v[42:45]
	v_mfma_f32_16x16x32_bf16 v[42:45], v[196:199], v[140:143], v[208:211]
	v_mfma_f32_16x16x32_bf16 v[58:61], v[220:223], v[144:147], v[46:49]
	v_mfma_f32_16x16x32_bf16 v[46:49], v[224:227], v[140:143], v[212:215]
	v_mfma_f32_16x16x32_bf16 v[62:65], v[224:227], v[240:243], v[200:203]
	v_mfma_f32_16x16x32_bf16 v[34:37], v[184:187], v[236:239], v[34:37]
	v_mfma_f32_16x16x32_bf16 v[38:41], v[192:195], v[236:239], v[38:41]
	v_mfma_f32_16x16x32_bf16 v[42:45], v[220:223], v[236:239], v[42:45]
	v_mfma_f32_16x16x32_bf16 v[46:49], v[232:235], v[236:239], v[46:49]
	v_mfma_f32_16x16x32_bf16 v[62:65], v[232:235], v[144:147], v[62:65]
	s_setprio 0
	v_readlane_b32 s4, v245, 33
	v_readlane_b32 s5, v245, 34
	s_and_b64 vcc, exec, s[4:5]
	s_barrier
	s_cbranch_vccz .LBB0_101
	s_barrier

; #define LDA(dst, b, h) for (int m = 0; m < 4; ++m) for (int k = 0; k < 2; ++k) \
;     dst[m][k] = *reinterpret_cast<const bf16x8*>((char*)SA(b, h) + lds_byte(wr * 64 + m * 16 + fr, k * 32 + fq * 8))
; #define LDB(dst, b, h) for (int n = 0; n < 2; ++n) for (int k = 0; k < 2; ++k) \
;     dst[n][k] = *reinterpret_cast<const bf16x8*>((char*)SB(b, h) + lds_byte(wc * 32 + n * 16 + fr, k * 32 + fq * 8))
; #define MMA(ai, bj, At, Bt_) do { __builtin_amdgcn_s_setprio(1); \
;     for (int m = 0; m < 4; ++m) for (int n = 0; n < 2; ++n) for (int k = 0; k < 2; ++k) \
;       acc[ai][bj][m][n] = __builtin_amdgcn_mfma_f32_16x16x32_bf16(At[m][k], Bt_[n][k], acc[ai][bj][m][n], 0, 0, 0); \
;     __builtin_amdgcn_s_setprio(0); } while (0)
; #define WAIT_L(n) asm volatile("s_waitcnt lgkmcnt(" #n ")" ::: "memory")
; #define BAR __builtin_amdgcn_s_barrier()
; #define SCHED __builtin_amdgcn_sched_barrier(0)
;     ...
;       LDB(B0, 0, 0); SCHED; LDA(At, 0, 0); STAGE(SA(1, 1), A, brow + HALF, t + 1);
;       WAIT_L(8); BAR; WAIT_L(0); MMA(0, 0, At, B0); BAR; SCHED;
;       LDB(B1, 0, 1); STAGE(SB(0, 0), Bt, bcol, t + 2);
;       BAR; WAIT_L(0); MMA(0, 1, At, B1); BAR;
;       LDA(At, 0, 1); STAGE(SA(0, 0), A, brow, t + 2);
;       BAR; WAIT_L(0); MMA(1, 0, At, B0); BAR; SCHED;
.LBB0_155:
	v_add_u32_e32 v143, s2, v142
	ds_read_b128 v[146:149], v143
	ds_read_b128 v[150:153], v143 offset:1024
	ds_read_b128 v[154:157], v143 offset:2048
	ds_read_b128 v[158:161], v143 offset:3072
	s_add_u32 s40, s30, s10
	s_addc_u32 s41, s31, s11
	s_add_u32 s42, s40, 0x80080
	s_addc_u32 s43, s41, 0
	s_add_i32 s39, s24, 0xc000
	ds_read_b128 v[162:165], v133
	ds_read_b128 v[184:187], v133 offset:1024
	ds_read_b128 v[188:191], v134
	ds_read_b128 v[192:195], v134 offset:1024
	ds_read_b128 v[196:199], v137
	ds_read_b128 v[200:203], v137 offset:1024
	ds_read_b128 v[204:207], v139
	ds_read_b128 v[208:211], v139 offset:1024
	s_mov_b32 m0, s39
	v_lshl_add_u64 v[144:145], s[42:43], 0, v[0:1]
	s_add_i32 s38, s24, 0xe000
	global_load_lds_dwordx4 v[144:145], off
	v_lshl_add_u64 v[144:145], s[42:43], 0, v[140:141]
	s_mov_b32 m0, s38
	s_nop 0
	global_load_lds_dwordx4 v[144:145], off
	s_waitcnt lgkmcnt(8)
	s_barrier
	s_waitcnt lgkmcnt(0)
	v_mfma_f32_16x16x32_bf16 v[126:129], v[162:165], v[146:149], v[126:129]
	v_mfma_f32_16x16x32_bf16 v[122:125], v[162:165], v[154:157], v[122:125]
	v_mfma_f32_16x16x32_bf16 v[118:121], v[188:191], v[146:149], v[118:121]
	v_mfma_f32_16x16x32_bf16 v[114:117], v[188:191], v[154:157], v[114:117]
	v_mfma_f32_16x16x32_bf16 v[110:113], v[196:199], v[146:149], v[110:113]
	v_mfma_f32_16x16x32_bf16 v[106:109], v[196:199], v[154:157], v[106:109]
	v_mfma_f32_16x16x32_bf16 v[102:105], v[204:207], v[146:149], v[102:105]
	v_mfma_f32_16x16x32_bf16 v[98:101], v[204:207], v[154:157], v[98:101]
	v_mfma_f32_16x16x32_bf16 v[126:129], v[184:187], v[150:153], v[126:129]
	v_mfma_f32_16x16x32_bf16 v[122:125], v[184:187], v[158:161], v[122:125]
	v_mfma_f32_16x16x32_bf16 v[118:121], v[192:195], v[150:153], v[118:121]
	v_mfma_f32_16x16x32_bf16 v[114:117], v[192:195], v[158:161], v[114:117]
	v_mfma_f32_16x16x32_bf16 v[110:113], v[200:203], v[150:153], v[110:113]
	v_mfma_f32_16x16x32_bf16 v[106:109], v[200:203], v[158:161], v[106:109]
	v_mfma_f32_16x16x32_bf16 v[102:105], v[208:211], v[150:153], v[102:105]
	v_mfma_f32_16x16x32_bf16 v[98:101], v[208:211], v[158:161], v[98:101]
	s_barrier
	s_add_u32 s42, s34, s10
	s_addc_u32 s43, s35, s11
	s_add_u32 s44, s42, 0x100
	v_add_u32_e32 v144, s76, v142
	s_addc_u32 s45, s43, 0
	s_mov_b32 m0, s25
	ds_read_b128 v[212:215], v144
	ds_read_b128 v[216:219], v144 offset:1024
	ds_read_b128 v[220:223], v144 offset:2048
	ds_read_b128 v[224:227], v144 offset:3072
	s_nop 0
	v_lshl_add_u64 v[166:167], s[44:45], 0, v[0:1]
	global_load_lds_dwordx4 v[166:167], off
	v_lshl_add_u64 v[166:167], s[44:45], 0, v[140:141]
	s_mov_b32 m0, s26
	s_nop 0
	global_load_lds_dwordx4 v[166:167], off
	s_barrier
	s_waitcnt lgkmcnt(0)
	v_mfma_f32_16x16x32_bf16 v[94:97], v[162:165], v[212:215], v[94:97]
	v_mfma_f32_16x16x32_bf16 v[90:93], v[162:165], v[220:223], v[90:93]
	v_mfma_f32_16x16x32_bf16 v[86:89], v[188:191], v[212:215], v[86:89]
	v_mfma_f32_16x16x32_bf16 v[82:85], v[188:191], v[220:223], v[82:85]
	v_mfma_f32_16x16x32_bf16 v[78:81], v[196:199], v[212:215], v[78:81]
	v_mfma_f32_16x16x32_bf16 v[74:77], v[196:199], v[220:223], v[74:77]
	v_mfma_f32_16x16x32_bf16 v[70:73], v[204:207], v[212:215], v[70:73]
	v_mfma_f32_16x16x32_bf16 v[66:69], v[204:207], v[220:223], v[66:69]
	v_mfma_f32_16x16x32_bf16 v[94:97], v[184:187], v[216:219], v[94:97]
	v_mfma_f32_16x16x32_bf16 v[90:93], v[184:187], v[224:227], v[90:93]
	v_mfma_f32_16x16x32_bf16 v[86:89], v[192:195], v[216:219], v[86:89]
	v_mfma_f32_16x16x32_bf16 v[82:85], v[192:195], v[224:227], v[82:85]
	v_mfma_f32_16x16x32_bf16 v[78:81], v[200:203], v[216:219], v[78:81]
	v_mfma_f32_16x16x32_bf16 v[74:77], v[200:203], v[224:227], v[74:77]
	v_mfma_f32_16x16x32_bf16 v[70:73], v[208:211], v[216:219], v[70:73]
	v_mfma_f32_16x16x32_bf16 v[66:69], v[208:211], v[224:227], v[66:69]
	s_add_u32 s44, s40, 0x100
	s_addc_u32 s45, s41, 0
	s_mov_b32 m0, s24
	s_barrier
	ds_read_b128 v[162:165], v133 offset:16384
	ds_read_b128 v[184:187], v133 offset:17408
	ds_read_b128 v[188:191], v134 offset:16384
	ds_read_b128 v[192:195], v134 offset:17408
	ds_read_b128 v[196:199], v137 offset:16384
	ds_read_b128 v[200:203], v137 offset:17408
	ds_read_b128 v[204:207], v139 offset:16384
	ds_read_b128 v[208:211], v139 offset:17408
	s_nop 0
	v_lshl_add_u64 v[166:167], s[44:45], 0, v[0:1]
	global_load_lds_dwordx4 v[166:167], off
	v_lshl_add_u64 v[166:167], s[44:45], 0, v[140:141]
	s_mov_b32 m0, s9
	s_nop 0
	global_load_lds_dwordx4 v[166:167], off
	s_barrier
	s_waitcnt lgkmcnt(0)
	v_mfma_f32_16x16x32_bf16 v[62:65], v[162:165], v[146:149], v[62:65]
	v_mfma_f32_16x16x32_bf16 v[58:61], v[162:165], v[154:157], v[58:61]
	v_mfma_f32_16x16x32_bf16 v[54:57], v[188:191], v[146:149], v[54:57]
	v_mfma_f32_16x16x32_bf16 v[50:53], v[188:191], v[154:157], v[50:53]
	v_mfma_f32_16x16x32_bf16 v[46:49], v[196:199], v[146:149], v[46:49]
	v_mfma_f32_16x16x32_bf16 v[42:45], v[196:199], v[154:157], v[42:45]
	v_mfma_f32_16x16x32_bf16 v[38:41], v[204:207], v[146:149], v[38:41]
	v_mfma_f32_16x16x32_bf16 v[34:37], v[204:207], v[154:157], v[34:37]
	v_mfma_f32_16x16x32_bf16 v[62:65], v[184:187], v[150:153], v[62:65]
	v_mfma_f32_16x16x32_bf16 v[58:61], v[184:187], v[158:161], v[58:61]
	v_mfma_f32_16x16x32_bf16 v[54:57], v[192:195], v[150:153], v[54:57]
	v_mfma_f32_16x16x32_bf16 v[50:53], v[192:195], v[158:161], v[50:53]
	v_mfma_f32_16x16x32_bf16 v[46:49], v[200:203], v[150:153], v[46:49]
	v_mfma_f32_16x16x32_bf16 v[42:45], v[200:203], v[158:161], v[42:45]
	v_mfma_f32_16x16x32_bf16 v[38:41], v[208:211], v[150:153], v[38:41]
	v_mfma_f32_16x16x32_bf16 v[34:37], v[208:211], v[158:161], v[34:37]
	s_barrier
; #define LDA(dst, b, h) for (int m = 0; m < 4; ++m) for (int k = 0; k < 2; ++k) \
;     dst[m][k] = *reinterpret_cast<const bf16x8*>((char*)SA(b, h) + lds_byte(wr * 64 + m * 16 + fr, k * 32 + fq * 8))
; #define LDB(dst, b, h) for (int n = 0; n < 2; ++n) for (int k = 0; k < 2; ++k) \
;     dst[n][k] = *reinterpret_cast<const bf16x8*>((char*)SB(b, h) + lds_byte(wc * 32 + n * 16 + fr, k * 32 + fq * 8))
; #define MMA(ai, bj, At, Bt_) do { __builtin_amdgcn_s_setprio(1); \
;     for (int m = 0; m < 4; ++m) for (int n = 0; n < 2; ++n) for (int k = 0; k < 2; ++k) \
;       acc[ai][bj][m][n] = __builtin_amdgcn_mfma_f32_16x16x32_bf16(At[m][k], Bt_[n][k], acc[ai][bj][m][n], 0, 0, 0); \
;     __builtin_amdgcn_s_setprio(0); } while (0)
; #define WAIT_V(n) asm volatile("s_waitcnt vmcnt(" #n ")" ::: "memory")
; #define WAIT_L(n) asm volatile("s_waitcnt lgkmcnt(" #n ")" ::: "memory")
; #define BAR __builtin_amdgcn_s_barrier()
; #define SCHED __builtin_amdgcn_sched_barrier(0)
;     ...
;       STAGE(SB(0, 1), Bt, bcol + HALF, t + 2);
;       WAIT_V(6); BAR; MMA(1, 1, At, B1); BAR;
;       LDB(B0, 1, 0); SCHED; LDA(At, 1, 0); STAGE(SA(0, 1), A, brow + HALF, t + 2);
;       WAIT_L(8); BAR; WAIT_L(0); MMA(0, 0, At, B0); BAR; SCHED;
;       LDB(B1, 1, 1); STAGE(SB(1, 0), Bt, bcol, t + 3);
;       BAR; WAIT_L(0); MMA(0, 1, At, B1); BAR;
;       LDA(At, 1, 1); STAGE(SA(1, 0), A, brow, t + 3);
	s_add_u32 s44, s42, 0x80100
	s_addc_u32 s45, s43, 0
	s_mov_b32 m0, s27
	s_nop 0
	v_lshl_add_u64 v[146:147], s[44:45], 0, v[0:1]
	global_load_lds_dwordx4 v[146:147], off
	v_lshl_add_u64 v[146:147], s[44:45], 0, v[140:141]
	s_mov_b32 m0, s28
	s_nop 0
	global_load_lds_dwordx4 v[146:147], off
	s_waitcnt vmcnt(6)
	s_barrier
	v_mfma_f32_16x16x32_bf16 v[30:33], v[162:165], v[212:215], v[30:33]
	v_mfma_f32_16x16x32_bf16 v[26:29], v[162:165], v[220:223], v[26:29]
	v_mfma_f32_16x16x32_bf16 v[22:25], v[188:191], v[212:215], v[22:25]
	v_mfma_f32_16x16x32_bf16 v[18:21], v[188:191], v[220:223], v[18:21]
	v_mfma_f32_16x16x32_bf16 v[14:17], v[196:199], v[212:215], v[14:17]
	v_mfma_f32_16x16x32_bf16 v[10:13], v[196:199], v[220:223], v[10:13]
	v_mfma_f32_16x16x32_bf16 v[6:9], v[204:207], v[212:215], v[6:9]
	v_mfma_f32_16x16x32_bf16 v[2:5], v[204:207], v[220:223], v[2:5]
	v_mfma_f32_16x16x32_bf16 v[30:33], v[184:187], v[216:219], v[30:33]
	v_mfma_f32_16x16x32_bf16 v[26:29], v[184:187], v[224:227], v[26:29]
	v_mfma_f32_16x16x32_bf16 v[22:25], v[192:195], v[216:219], v[22:25]
	v_mfma_f32_16x16x32_bf16 v[18:21], v[192:195], v[224:227], v[18:21]
	v_mfma_f32_16x16x32_bf16 v[14:17], v[200:203], v[216:219], v[14:17]
	v_mfma_f32_16x16x32_bf16 v[10:13], v[200:203], v[224:227], v[10:13]
	v_mfma_f32_16x16x32_bf16 v[6:9], v[208:211], v[216:219], v[6:9]
	v_mfma_f32_16x16x32_bf16 v[2:5], v[208:211], v[224:227], v[2:5]
	v_add_u32_e32 v145, s77, v142
	s_barrier
	ds_read_b128 v[148:151], v145
	ds_read_b128 v[152:155], v145 offset:1024
	ds_read_b128 v[156:159], v145 offset:2048
	ds_read_b128 v[160:163], v145 offset:3072
	s_add_u32 s44, s40, 0x80100
	s_addc_u32 s45, s41, 0
	s_mov_b32 m0, s7
	ds_read_b128 v[164:167], v133 offset:32768
	ds_read_b128 v[184:187], v133 offset:33792
	ds_read_b128 v[188:191], v134 offset:32768
	ds_read_b128 v[192:195], v134 offset:33792
	ds_read_b128 v[196:199], v137 offset:32768
	ds_read_b128 v[200:203], v137 offset:33792
	ds_read_b128 v[204:207], v139 offset:32768
	ds_read_b128 v[208:211], v139 offset:33792
	s_nop 0
	v_lshl_add_u64 v[146:147], s[44:45], 0, v[0:1]
	global_load_lds_dwordx4 v[146:147], off
	v_lshl_add_u64 v[146:147], s[44:45], 0, v[140:141]
	s_mov_b32 m0, s29
	s_nop 0
	global_load_lds_dwordx4 v[146:147], off
	s_waitcnt lgkmcnt(8)
	s_barrier
	s_waitcnt lgkmcnt(0)
	v_mfma_f32_16x16x32_bf16 v[126:129], v[164:167], v[148:151], v[126:129]
	v_mfma_f32_16x16x32_bf16 v[122:125], v[164:167], v[156:159], v[122:125]
	v_mfma_f32_16x16x32_bf16 v[118:121], v[188:191], v[148:151], v[118:121]
	v_mfma_f32_16x16x32_bf16 v[114:117], v[188:191], v[156:159], v[114:117]
	v_mfma_f32_16x16x32_bf16 v[110:113], v[196:199], v[148:151], v[110:113]
	v_mfma_f32_16x16x32_bf16 v[106:109], v[196:199], v[156:159], v[106:109]
	v_mfma_f32_16x16x32_bf16 v[102:105], v[204:207], v[148:151], v[102:105]
	v_mfma_f32_16x16x32_bf16 v[98:101], v[204:207], v[156:159], v[98:101]
	v_mfma_f32_16x16x32_bf16 v[126:129], v[184:187], v[152:155], v[126:129]
	v_mfma_f32_16x16x32_bf16 v[122:125], v[184:187], v[160:163], v[122:125]
	v_mfma_f32_16x16x32_bf16 v[118:121], v[192:195], v[152:155], v[118:121]
	v_mfma_f32_16x16x32_bf16 v[114:117], v[192:195], v[160:163], v[114:117]
	v_mfma_f32_16x16x32_bf16 v[110:113], v[200:203], v[152:155], v[110:113]
	v_mfma_f32_16x16x32_bf16 v[106:109], v[200:203], v[160:163], v[106:109]
	v_mfma_f32_16x16x32_bf16 v[102:105], v[208:211], v[152:155], v[102:105]
	v_mfma_f32_16x16x32_bf16 v[98:101], v[208:211], v[160:163], v[98:101]
	s_barrier
	s_add_u32 s44, s42, 0x180
	v_add_u32_e32 v146, s78, v142
	s_addc_u32 s45, s43, 0
	s_mov_b32 m0, s12
	ds_read_b128 v[212:215], v146
	ds_read_b128 v[216:219], v146 offset:1024
	ds_read_b128 v[220:223], v146 offset:2048
	ds_read_b128 v[224:227], v146 offset:3072
	s_nop 0
	v_lshl_add_u64 v[228:229], s[44:45], 0, v[0:1]
	global_load_lds_dwordx4 v[228:229], off
	v_lshl_add_u64 v[228:229], s[44:45], 0, v[140:141]
	s_mov_b32 m0, s13
	s_nop 0
	global_load_lds_dwordx4 v[228:229], off
	s_barrier
	s_waitcnt lgkmcnt(0)
	v_mfma_f32_16x16x32_bf16 v[94:97], v[164:167], v[212:215], v[94:97]
	v_mfma_f32_16x16x32_bf16 v[90:93], v[164:167], v[220:223], v[90:93]
	v_mfma_f32_16x16x32_bf16 v[86:89], v[188:191], v[212:215], v[86:89]
	v_mfma_f32_16x16x32_bf16 v[82:85], v[188:191], v[220:223], v[82:85]
	v_mfma_f32_16x16x32_bf16 v[78:81], v[196:199], v[212:215], v[78:81]
	v_mfma_f32_16x16x32_bf16 v[74:77], v[196:199], v[220:223], v[74:77]
	v_mfma_f32_16x16x32_bf16 v[70:73], v[204:207], v[212:215], v[70:73]
	v_mfma_f32_16x16x32_bf16 v[66:69], v[204:207], v[220:223], v[66:69]
	v_mfma_f32_16x16x32_bf16 v[94:97], v[184:187], v[216:219], v[94:97]
	v_mfma_f32_16x16x32_bf16 v[90:93], v[184:187], v[224:227], v[90:93]
	v_mfma_f32_16x16x32_bf16 v[86:89], v[192:195], v[216:219], v[86:89]
	v_mfma_f32_16x16x32_bf16 v[82:85], v[192:195], v[224:227], v[82:85]
	v_mfma_f32_16x16x32_bf16 v[78:81], v[200:203], v[216:219], v[78:81]
	v_mfma_f32_16x16x32_bf16 v[74:77], v[200:203], v[224:227], v[74:77]
	v_mfma_f32_16x16x32_bf16 v[70:73], v[208:211], v[216:219], v[70:73]
	v_mfma_f32_16x16x32_bf16 v[66:69], v[208:211], v[224:227], v[66:69]
	s_add_u32 s40, s40, 0x180
	s_addc_u32 s41, s41, 0
	s_mov_b32 m0, s14
	s_barrier
	ds_read_b128 v[164:167], v133 offset:49152
	ds_read_b128 v[184:187], v133 offset:50176
	ds_read_b128 v[188:191], v134 offset:49152
	ds_read_b128 v[192:195], v134 offset:50176
	ds_read_b128 v[196:199], v137 offset:49152
	ds_read_b128 v[200:203], v137 offset:50176
	ds_read_b128 v[204:207], v139 offset:49152
	ds_read_b128 v[208:211], v139 offset:50176
	s_nop 0
	v_lshl_add_u64 v[228:229], s[40:41], 0, v[0:1]
	global_load_lds_dwordx4 v[228:229], off
	v_lshl_add_u64 v[228:229], s[40:41], 0, v[140:141]
	s_mov_b32 m0, s15
	s_nop 0
	global_load_lds_dwordx4 v[228:229], off
	s_barrier
; #define LDA(dst, b, h) for (int m = 0; m < 4; ++m) for (int k = 0; k < 2; ++k) \
;     dst[m][k] = *reinterpret_cast<const bf16x8*>((char*)SA(b, h) + lds_byte(wr * 64 + m * 16 + fr, k * 32 + fq * 8))
; #define LDB(dst, b, h) for (int n = 0; n < 2; ++n) for (int k = 0; k < 2; ++k) \
;     dst[n][k] = *reinterpret_cast<const bf16x8*>((char*)SB(b, h) + lds_byte(wc * 32 + n * 16 + fr, k * 32 + fq * 8))
; #define MMA(ai, bj, At, Bt_) do { __builtin_amdgcn_s_setprio(1); \
;     for (int m = 0; m < 4; ++m) for (int n = 0; n < 2; ++n) for (int k = 0; k < 2; ++k) \
;       acc[ai][bj][m][n] = __builtin_amdgcn_mfma_f32_16x16x32_bf16(At[m][k], Bt_[n][k], acc[ai][bj][m][n], 0, 0, 0); \
;     __builtin_amdgcn_s_setprio(0); } while (0)
; #define WAIT_V(n) asm volatile("s_waitcnt vmcnt(" #n ")" ::: "memory")
; #define WAIT_L(n) asm volatile("s_waitcnt lgkmcnt(" #n ")" ::: "memory")
; #define BAR __builtin_amdgcn_s_barrier()
; #define SCHED __builtin_amdgcn_sched_barrier(0)
;     ...
;       BAR; WAIT_L(0); MMA(1, 0, At, B0); BAR; SCHED;
;       STAGE(SB(1, 1), Bt, bcol + HALF, t + 3);
;       WAIT_V(6); BAR; MMA(1, 1, At, B1); BAR;
;     }
;     { LDB(B0, 0, 0); LDA(At, 0, 0); STAGE(SA(1, 1), A, brow + HALF, nt - 1);
;       BAR; WAIT_L(0); MMA(0, 0, At, B0); BAR;
;       LDB(B1, 0, 1); BAR; WAIT_L(0); MMA(0, 1, At, B1); BAR;
	s_waitcnt lgkmcnt(0)
	v_mfma_f32_16x16x32_bf16 v[62:65], v[164:167], v[148:151], v[62:65]
	v_mfma_f32_16x16x32_bf16 v[58:61], v[164:167], v[156:159], v[58:61]
	v_mfma_f32_16x16x32_bf16 v[54:57], v[188:191], v[148:151], v[54:57]
	v_mfma_f32_16x16x32_bf16 v[50:53], v[188:191], v[156:159], v[50:53]
	v_mfma_f32_16x16x32_bf16 v[46:49], v[196:199], v[148:151], v[46:49]
	v_mfma_f32_16x16x32_bf16 v[42:45], v[196:199], v[156:159], v[42:45]
	v_mfma_f32_16x16x32_bf16 v[38:41], v[204:207], v[148:151], v[38:41]
	v_mfma_f32_16x16x32_bf16 v[34:37], v[204:207], v[156:159], v[34:37]
	v_mfma_f32_16x16x32_bf16 v[62:65], v[184:187], v[152:155], v[62:65]
	v_mfma_f32_16x16x32_bf16 v[58:61], v[184:187], v[160:163], v[58:61]
	v_mfma_f32_16x16x32_bf16 v[54:57], v[192:195], v[152:155], v[54:57]
	v_mfma_f32_16x16x32_bf16 v[50:53], v[192:195], v[160:163], v[50:53]
	v_mfma_f32_16x16x32_bf16 v[46:49], v[200:203], v[152:155], v[46:49]
	v_mfma_f32_16x16x32_bf16 v[42:45], v[200:203], v[160:163], v[42:45]
	v_mfma_f32_16x16x32_bf16 v[38:41], v[208:211], v[152:155], v[38:41]
	v_mfma_f32_16x16x32_bf16 v[34:37], v[208:211], v[160:163], v[34:37]
	s_barrier
	s_add_u32 s40, s42, 0x80180
	s_addc_u32 s41, s43, 0
	s_mov_b32 m0, s16
	s_nop 0
	v_lshl_add_u64 v[148:149], s[40:41], 0, v[0:1]
	global_load_lds_dwordx4 v[148:149], off
	v_lshl_add_u64 v[148:149], s[40:41], 0, v[140:141]
	s_mov_b32 m0, s17
	s_nop 0
	global_load_lds_dwordx4 v[148:149], off
	s_waitcnt vmcnt(6)
	s_barrier
	v_mfma_f32_16x16x32_bf16 v[30:33], v[164:167], v[212:215], v[30:33]
	v_mfma_f32_16x16x32_bf16 v[26:29], v[164:167], v[220:223], v[26:29]
	v_mfma_f32_16x16x32_bf16 v[22:25], v[188:191], v[212:215], v[22:25]
	v_mfma_f32_16x16x32_bf16 v[18:21], v[188:191], v[220:223], v[18:21]
	v_mfma_f32_16x16x32_bf16 v[14:17], v[196:199], v[212:215], v[14:17]
	v_mfma_f32_16x16x32_bf16 v[10:13], v[196:199], v[220:223], v[10:13]
	v_mfma_f32_16x16x32_bf16 v[6:9], v[204:207], v[212:215], v[6:9]
	v_mfma_f32_16x16x32_bf16 v[2:5], v[204:207], v[220:223], v[2:5]
	v_mfma_f32_16x16x32_bf16 v[30:33], v[184:187], v[216:219], v[30:33]
	v_mfma_f32_16x16x32_bf16 v[26:29], v[184:187], v[224:227], v[26:29]
	v_mfma_f32_16x16x32_bf16 v[22:25], v[192:195], v[216:219], v[22:25]
	v_mfma_f32_16x16x32_bf16 v[18:21], v[192:195], v[224:227], v[18:21]
	v_mfma_f32_16x16x32_bf16 v[14:17], v[200:203], v[216:219], v[14:17]
	v_mfma_f32_16x16x32_bf16 v[10:13], v[200:203], v[224:227], v[10:13]
	v_mfma_f32_16x16x32_bf16 v[6:9], v[208:211], v[216:219], v[6:9]
	v_mfma_f32_16x16x32_bf16 v[2:5], v[208:211], v[224:227], v[2:5]
	s_add_i32 s37, s37, 2
	s_add_u32 s10, s10, 0x100
	s_addc_u32 s11, s11, 0
	s_cmp_gt_u32 s37, 27
	s_barrier
	s_cbranch_scc0 .LBB0_155
	s_add_u32 s4, s4, 0xf80
	s_addc_u32 s5, s5, 0
	s_mov_b32 m0, s39
	ds_read_b128 v[148:151], v143
	ds_read_b128 v[152:155], v143 offset:1024
	ds_read_b128 v[156:159], v143 offset:2048
	ds_read_b128 v[160:163], v143 offset:3072
	ds_read_b128 v[164:167], v133
	ds_read_b128 v[184:187], v133 offset:1024
	ds_read_b128 v[188:191], v134
	ds_read_b128 v[192:195], v134 offset:1024
	ds_read_b128 v[196:199], v137
	ds_read_b128 v[200:203], v137 offset:1024
	ds_read_b128 v[204:207], v139
	ds_read_b128 v[208:211], v139 offset:1024
	s_nop 0
	v_lshl_add_u64 v[142:143], s[4:5], 0, v[0:1]
	global_load_lds_dwordx4 v[142:143], off
	v_lshl_add_u64 v[140:141], s[4:5], 0, v[140:141]
	s_mov_b32 m0, s38
	s_nop 0
	global_load_lds_dwordx4 v[140:141], off
	s_barrier
	s_waitcnt lgkmcnt(0)
	s_setprio 1
	s_waitcnt lgkmcnt(0)
	v_mfma_f32_16x16x32_bf16 v[126:129], v[164:167], v[148:151], v[126:129]
	v_mfma_f32_16x16x32_bf16 v[118:121], v[188:191], v[148:151], v[118:121]
	v_mfma_f32_16x16x32_bf16 v[110:113], v[196:199], v[148:151], v[110:113]
	v_mfma_f32_16x16x32_bf16 v[102:105], v[204:207], v[148:151], v[102:105]
	v_mfma_f32_16x16x32_bf16 v[126:129], v[184:187], v[152:155], v[126:129]
	v_mfma_f32_16x16x32_bf16 v[122:125], v[164:167], v[156:159], v[122:125]
	v_mfma_f32_16x16x32_bf16 v[118:121], v[192:195], v[152:155], v[118:121]
	v_mfma_f32_16x16x32_bf16 v[114:117], v[188:191], v[156:159], v[114:117]
	v_mfma_f32_16x16x32_bf16 v[110:113], v[200:203], v[152:155], v[110:113]
	v_mfma_f32_16x16x32_bf16 v[106:109], v[196:199], v[156:159], v[106:109]
	v_mfma_f32_16x16x32_bf16 v[102:105], v[208:211], v[152:155], v[102:105]
	v_mfma_f32_16x16x32_bf16 v[98:101], v[204:207], v[156:159], v[98:101]
	v_mfma_f32_16x16x32_bf16 v[140:143], v[184:187], v[160:163], v[122:125]
	v_mfma_f32_16x16x32_bf16 v[212:215], v[192:195], v[160:163], v[114:117]
	v_mfma_f32_16x16x32_bf16 v[216:219], v[200:203], v[160:163], v[106:109]
	v_mfma_f32_16x16x32_bf16 v[220:223], v[208:211], v[160:163], v[98:101]
	s_setprio 0
	s_barrier
	s_nop 1
	ds_read_b128 v[98:101], v144
	ds_read_b128 v[106:109], v144 offset:1024
	ds_read_b128 v[114:117], v144 offset:2048
	ds_read_b128 v[122:125], v144 offset:3072
	s_barrier
	s_waitcnt lgkmcnt(0)
	s_setprio 1
	s_waitcnt lgkmcnt(0)
	v_mfma_f32_16x16x32_bf16 v[94:97], v[164:167], v[98:101], v[94:97]
	v_mfma_f32_16x16x32_bf16 v[86:89], v[188:191], v[98:101], v[86:89]
	v_mfma_f32_16x16x32_bf16 v[78:81], v[196:199], v[98:101], v[78:81]
	v_mfma_f32_16x16x32_bf16 v[70:73], v[204:207], v[98:101], v[70:73]
	v_mfma_f32_16x16x32_bf16 v[94:97], v[184:187], v[106:109], v[94:97]
	v_mfma_f32_16x16x32_bf16 v[90:93], v[164:167], v[114:117], v[90:93]
	v_mfma_f32_16x16x32_bf16 v[86:89], v[192:195], v[106:109], v[86:89]
	v_mfma_f32_16x16x32_bf16 v[82:85], v[188:191], v[114:117], v[82:85]
	v_mfma_f32_16x16x32_bf16 v[78:81], v[200:203], v[106:109], v[78:81]
	v_mfma_f32_16x16x32_bf16 v[74:77], v[196:199], v[114:117], v[74:77]
	v_mfma_f32_16x16x32_bf16 v[70:73], v[208:211], v[106:109], v[70:73]
	v_mfma_f32_16x16x32_bf16 v[66:69], v[204:207], v[114:117], v[66:69]
	v_mfma_f32_16x16x32_bf16 v[164:167], v[184:187], v[122:125], v[90:93]
	v_mfma_f32_16x16x32_bf16 v[184:187], v[192:195], v[122:125], v[82:85]
	v_mfma_f32_16x16x32_bf16 v[188:191], v[200:203], v[122:125], v[74:77]
	v_mfma_f32_16x16x32_bf16 v[192:195], v[208:211], v[122:125], v[66:69]
	s_setprio 0
	s_barrier
; #define LDA(dst, b, h) for (int m = 0; m < 4; ++m) for (int k = 0; k < 2; ++k) \
;     dst[m][k] = *reinterpret_cast<const bf16x8*>((char*)SA(b, h) + lds_byte(wr * 64 + m * 16 + fr, k * 32 + fq * 8))
; #define LDB(dst, b, h) for (int n = 0; n < 2; ++n) for (int k = 0; k < 2; ++k) \
;     dst[n][k] = *reinterpret_cast<const bf16x8*>((char*)SB(b, h) + lds_byte(wc * 32 + n * 16 + fr, k * 32 + fq * 8))
; #define MMA(ai, bj, At, Bt_) do { __builtin_amdgcn_s_setprio(1); \
;     for (int m = 0; m < 4; ++m) for (int n = 0; n < 2; ++n) for (int k = 0; k < 2; ++k) \
;       acc[ai][bj][m][n] = __builtin_amdgcn_mfma_f32_16x16x32_bf16(At[m][k], Bt_[n][k], acc[ai][bj][m][n], 0, 0, 0); \
;     __builtin_amdgcn_s_setprio(0); } while (0)
; #define WAIT_V(n) asm volatile("s_waitcnt vmcnt(" #n ")" ::: "memory")
; #define WAIT_L(n) asm volatile("s_waitcnt lgkmcnt(" #n ")" ::: "memory")
; #define BAR __builtin_amdgcn_s_barrier()
;     ...
;       LDA(At, 0, 1); WAIT_V(4); BAR; WAIT_L(0); MMA(1, 0, At, B0); MMA(1, 1, At, B1); BAR; }
;     { LDB(B0, 1, 0); LDA(At, 1, 0); WAIT_V(2); BAR; WAIT_L(0); MMA(0, 0, At, B0); BAR;
	s_nop 1
	ds_read_b128 v[66:69], v133 offset:16384
	ds_read_b128 v[74:77], v133 offset:17408
	ds_read_b128 v[82:85], v134 offset:16384
	ds_read_b128 v[90:93], v134 offset:17408
	ds_read_b128 v[196:199], v137 offset:16384
	ds_read_b128 v[200:203], v137 offset:17408
	ds_read_b128 v[204:207], v139 offset:16384
	ds_read_b128 v[208:211], v139 offset:17408
	s_waitcnt vmcnt(4)
	s_barrier
	s_waitcnt lgkmcnt(0)
	s_setprio 1
	s_waitcnt lgkmcnt(0)
	v_mfma_f32_16x16x32_bf16 v[62:65], v[66:69], v[148:151], v[62:65]
	v_mfma_f32_16x16x32_bf16 v[54:57], v[82:85], v[148:151], v[54:57]
	v_mfma_f32_16x16x32_bf16 v[46:49], v[196:199], v[148:151], v[46:49]
	v_mfma_f32_16x16x32_bf16 v[38:41], v[204:207], v[148:151], v[38:41]
	v_mfma_f32_16x16x32_bf16 v[62:65], v[74:77], v[152:155], v[62:65]
	v_mfma_f32_16x16x32_bf16 v[58:61], v[66:69], v[156:159], v[58:61]
	v_mfma_f32_16x16x32_bf16 v[54:57], v[90:93], v[152:155], v[54:57]
	v_mfma_f32_16x16x32_bf16 v[50:53], v[82:85], v[156:159], v[50:53]
	v_mfma_f32_16x16x32_bf16 v[46:49], v[200:203], v[152:155], v[46:49]
	v_mfma_f32_16x16x32_bf16 v[42:45], v[196:199], v[156:159], v[42:45]
	v_mfma_f32_16x16x32_bf16 v[38:41], v[208:211], v[152:155], v[38:41]
	v_mfma_f32_16x16x32_bf16 v[34:37], v[204:207], v[156:159], v[34:37]
	v_mfma_f32_16x16x32_bf16 v[224:227], v[74:77], v[160:163], v[58:61]
	v_mfma_f32_16x16x32_bf16 v[228:231], v[90:93], v[160:163], v[50:53]
	v_mfma_f32_16x16x32_bf16 v[232:235], v[200:203], v[160:163], v[42:45]
	v_mfma_f32_16x16x32_bf16 v[148:151], v[208:211], v[160:163], v[34:37]
	s_setprio 0
	s_setprio 1
	v_mfma_f32_16x16x32_bf16 v[30:33], v[66:69], v[98:101], v[30:33]
	v_mfma_f32_16x16x32_bf16 v[22:25], v[82:85], v[98:101], v[22:25]
	v_mfma_f32_16x16x32_bf16 v[14:17], v[196:199], v[98:101], v[14:17]
	v_mfma_f32_16x16x32_bf16 v[6:9], v[204:207], v[98:101], v[6:9]
	v_mfma_f32_16x16x32_bf16 v[30:33], v[74:77], v[106:109], v[30:33]
	v_mfma_f32_16x16x32_bf16 v[26:29], v[66:69], v[114:117], v[26:29]
	v_mfma_f32_16x16x32_bf16 v[22:25], v[90:93], v[106:109], v[22:25]
	v_mfma_f32_16x16x32_bf16 v[18:21], v[82:85], v[114:117], v[18:21]
	v_mfma_f32_16x16x32_bf16 v[14:17], v[200:203], v[106:109], v[14:17]
	v_mfma_f32_16x16x32_bf16 v[10:13], v[196:199], v[114:117], v[10:13]
	v_mfma_f32_16x16x32_bf16 v[6:9], v[208:211], v[106:109], v[6:9]
	v_mfma_f32_16x16x32_bf16 v[2:5], v[204:207], v[114:117], v[2:5]
	v_mfma_f32_16x16x32_bf16 v[152:155], v[74:77], v[122:125], v[26:29]
	v_mfma_f32_16x16x32_bf16 v[156:159], v[90:93], v[122:125], v[18:21]
	v_mfma_f32_16x16x32_bf16 v[160:163], v[200:203], v[122:125], v[10:13]
	v_mfma_f32_16x16x32_bf16 v[196:199], v[208:211], v[122:125], v[2:5]
	s_setprio 0
	s_barrier
	s_nop 1
	ds_read_b128 v[2:5], v145
	ds_read_b128 v[10:13], v145 offset:1024
	ds_read_b128 v[200:203], v145 offset:2048
	ds_read_b128 v[204:207], v145 offset:3072
	ds_read_b128 v[18:21], v133 offset:32768
	ds_read_b128 v[26:29], v133 offset:33792
	ds_read_b128 v[34:37], v134 offset:32768
	ds_read_b128 v[42:45], v134 offset:33792
	ds_read_b128 v[50:53], v137 offset:32768
	ds_read_b128 v[58:61], v137 offset:33792
	ds_read_b128 v[208:211], v139 offset:32768
	ds_read_b128 v[236:239], v139 offset:33792
	s_waitcnt vmcnt(2)
	s_barrier
	s_waitcnt lgkmcnt(0)
	s_setprio 1
	s_waitcnt lgkmcnt(0)
	v_mfma_f32_16x16x32_bf16 v[66:69], v[18:21], v[2:5], v[126:129]
	v_mfma_f32_16x16x32_bf16 v[122:125], v[26:29], v[10:13], v[66:69]
	v_mfma_f32_16x16x32_bf16 v[66:69], v[18:21], v[200:203], v[140:143]
	v_mfma_f32_16x16x32_bf16 v[114:117], v[26:29], v[204:207], v[66:69]
	v_mfma_f32_16x16x32_bf16 v[66:69], v[34:37], v[2:5], v[118:121]
	v_mfma_f32_16x16x32_bf16 v[106:109], v[42:45], v[10:13], v[66:69]
	v_mfma_f32_16x16x32_bf16 v[66:69], v[34:37], v[200:203], v[212:215]
	v_mfma_f32_16x16x32_bf16 v[98:101], v[42:45], v[204:207], v[66:69]
	v_mfma_f32_16x16x32_bf16 v[66:69], v[50:53], v[2:5], v[110:113]
	v_mfma_f32_16x16x32_bf16 v[90:93], v[58:61], v[10:13], v[66:69]
	v_mfma_f32_16x16x32_bf16 v[66:69], v[50:53], v[200:203], v[216:219]
	v_mfma_f32_16x16x32_bf16 v[82:85], v[58:61], v[204:207], v[66:69]
	v_mfma_f32_16x16x32_bf16 v[66:69], v[208:211], v[2:5], v[102:105]
	v_mfma_f32_16x16x32_bf16 v[74:77], v[236:239], v[10:13], v[66:69]
	v_mfma_f32_16x16x32_bf16 v[66:69], v[208:211], v[200:203], v[220:223]
	v_mfma_f32_16x16x32_bf16 v[66:69], v[236:239], v[204:207], v[66:69]
	s_setprio 0
	s_barrier
; #define LDA(dst, b, h) for (int m = 0; m < 4; ++m) for (int k = 0; k < 2; ++k) \
;     dst[m][k] = *reinterpret_cast<const bf16x8*>((char*)SA(b, h) + lds_byte(wr * 64 + m * 16 + fr, k * 32 + fq * 8))
; #define LDB(dst, b, h) for (int n = 0; n < 2; ++n) for (int k = 0; k < 2; ++k) \
;     dst[n][k] = *reinterpret_cast<const bf16x8*>((char*)SB(b, h) + lds_byte(wc * 32 + n * 16 + fr, k * 32 + fq * 8))
; #define MMA(ai, bj, At, Bt_) do { __builtin_amdgcn_s_setprio(1); \
;     for (int m = 0; m < 4; ++m) for (int n = 0; n < 2; ++n) for (int k = 0; k < 2; ++k) \
;       acc[ai][bj][m][n] = __builtin_amdgcn_mfma_f32_16x16x32_bf16(At[m][k], Bt_[n][k], acc[ai][bj][m][n], 0, 0, 0); \
;     __builtin_amdgcn_s_setprio(0); } while (0)
; #define WAIT_V(n) asm volatile("s_waitcnt vmcnt(" #n ")" ::: "memory")
; #define WAIT_L(n) asm volatile("s_waitcnt lgkmcnt(" #n ")" ::: "memory")
; #define BAR __builtin_amdgcn_s_barrier()
;     ...
;       LDB(B1, 1, 1); WAIT_V(0); BAR; WAIT_L(0); MMA(0, 1, At, B1); BAR;
;       LDA(At, 1, 1); BAR; WAIT_L(0); MMA(1, 0, At, B0); MMA(1, 1, At, B1); BAR; }
;     if (wr == 0) BAR;
	ds_read_b128 v[140:143], v146
	ds_read_b128 v[212:215], v146 offset:1024
	ds_read_b128 v[216:219], v146 offset:2048
	ds_read_b128 v[144:147], v146 offset:3072
	s_waitcnt vmcnt(0)
	s_barrier
	s_waitcnt lgkmcnt(0)
	s_setprio 1
	s_waitcnt lgkmcnt(0)
	v_mfma_f32_16x16x32_bf16 v[94:97], v[18:21], v[140:143], v[94:97]
	v_mfma_f32_16x16x32_bf16 v[18:21], v[18:21], v[216:219], v[164:167]
	v_mfma_f32_16x16x32_bf16 v[118:121], v[26:29], v[144:147], v[18:21]
	v_mfma_f32_16x16x32_bf16 v[18:21], v[34:37], v[140:143], v[86:89]
	v_mfma_f32_16x16x32_bf16 v[110:113], v[42:45], v[212:215], v[18:21]
	v_mfma_f32_16x16x32_bf16 v[18:21], v[34:37], v[216:219], v[184:187]
	v_mfma_f32_16x16x32_bf16 v[102:105], v[42:45], v[144:147], v[18:21]
	v_mfma_f32_16x16x32_bf16 v[18:21], v[50:53], v[140:143], v[78:81]
	v_mfma_f32_16x16x32_bf16 v[126:129], v[26:29], v[212:215], v[94:97]
	v_mfma_f32_16x16x32_bf16 v[94:97], v[58:61], v[212:215], v[18:21]
	v_mfma_f32_16x16x32_bf16 v[18:21], v[50:53], v[216:219], v[188:191]
	v_mfma_f32_16x16x32_bf16 v[86:89], v[58:61], v[144:147], v[18:21]
	v_mfma_f32_16x16x32_bf16 v[18:21], v[208:211], v[140:143], v[70:73]
	v_mfma_f32_16x16x32_bf16 v[78:81], v[236:239], v[212:215], v[18:21]
	v_mfma_f32_16x16x32_bf16 v[18:21], v[208:211], v[216:219], v[192:195]
	v_mfma_f32_16x16x32_bf16 v[70:73], v[236:239], v[144:147], v[18:21]
	s_setprio 0
	s_barrier
	ds_read_b128 v[164:167], v133 offset:49152
	ds_read_b128 v[184:187], v133 offset:50176
	ds_read_b128 v[188:191], v134 offset:49152
	ds_read_b128 v[192:195], v134 offset:50176
	ds_read_b128 v[208:211], v137 offset:49152
	ds_read_b128 v[220:223], v137 offset:50176
	ds_read_b128 v[236:239], v139 offset:49152
	ds_read_b128 v[240:243], v139 offset:50176
	s_barrier
	s_waitcnt lgkmcnt(0)
	s_setprio 1
	s_waitcnt lgkmcnt(0)
	v_mfma_f32_16x16x32_bf16 v[18:21], v[164:167], v[2:5], v[62:65]
	v_mfma_f32_16x16x32_bf16 v[58:61], v[184:187], v[10:13], v[18:21]
	v_mfma_f32_16x16x32_bf16 v[18:21], v[164:167], v[200:203], v[224:227]
	v_mfma_f32_16x16x32_bf16 v[50:53], v[184:187], v[204:207], v[18:21]
	v_mfma_f32_16x16x32_bf16 v[18:21], v[188:191], v[2:5], v[54:57]
	v_mfma_f32_16x16x32_bf16 v[42:45], v[192:195], v[10:13], v[18:21]
	v_mfma_f32_16x16x32_bf16 v[18:21], v[188:191], v[200:203], v[228:231]
	v_mfma_f32_16x16x32_bf16 v[34:37], v[192:195], v[204:207], v[18:21]
	v_mfma_f32_16x16x32_bf16 v[18:21], v[208:211], v[2:5], v[46:49]
	v_mfma_f32_16x16x32_bf16 v[2:5], v[236:239], v[2:5], v[38:41]
	v_mfma_f32_16x16x32_bf16 v[26:29], v[220:223], v[10:13], v[18:21]
	v_mfma_f32_16x16x32_bf16 v[18:21], v[208:211], v[200:203], v[232:235]
	v_mfma_f32_16x16x32_bf16 v[10:13], v[240:243], v[10:13], v[2:5]
	v_mfma_f32_16x16x32_bf16 v[2:5], v[236:239], v[200:203], v[148:151]
	v_mfma_f32_16x16x32_bf16 v[18:21], v[220:223], v[204:207], v[18:21]
	v_mfma_f32_16x16x32_bf16 v[2:5], v[240:243], v[204:207], v[2:5]
	s_setprio 0
	s_setprio 1
	v_mfma_f32_16x16x32_bf16 v[30:33], v[164:167], v[140:143], v[30:33]
	v_mfma_f32_16x16x32_bf16 v[62:65], v[184:187], v[212:215], v[30:33]
	v_mfma_f32_16x16x32_bf16 v[30:33], v[164:167], v[216:219], v[152:155]
	v_mfma_f32_16x16x32_bf16 v[22:25], v[188:191], v[140:143], v[22:25]
	v_mfma_f32_16x16x32_bf16 v[14:17], v[208:211], v[140:143], v[14:17]
	v_mfma_f32_16x16x32_bf16 v[54:57], v[184:187], v[144:147], v[30:33]
	v_mfma_f32_16x16x32_bf16 v[46:49], v[192:195], v[212:215], v[22:25]
	v_mfma_f32_16x16x32_bf16 v[22:25], v[188:191], v[216:219], v[156:159]
	v_mfma_f32_16x16x32_bf16 v[30:33], v[220:223], v[212:215], v[14:17]
	v_mfma_f32_16x16x32_bf16 v[14:17], v[208:211], v[216:219], v[160:163]
	v_mfma_f32_16x16x32_bf16 v[6:9], v[236:239], v[140:143], v[6:9]
	v_mfma_f32_16x16x32_bf16 v[38:41], v[192:195], v[144:147], v[22:25]
	v_mfma_f32_16x16x32_bf16 v[22:25], v[220:223], v[144:147], v[14:17]
	v_mfma_f32_16x16x32_bf16 v[14:17], v[240:243], v[212:215], v[6:9]
	v_mfma_f32_16x16x32_bf16 v[6:9], v[236:239], v[216:219], v[196:199]
	v_mfma_f32_16x16x32_bf16 v[6:9], v[240:243], v[144:147], v[6:9]
	s_setprio 0
	v_readlane_b32 s4, v245, 33
	v_readlane_b32 s5, v245, 34
	s_and_b64 vcc, exec, s[4:5]
	s_barrier
	s_cbranch_vccz .LBB0_158
	s_barrier

; #define LDA(dst, b, h) for (int m = 0; m < 4; ++m) for (int k = 0; k < 2; ++k) \
;     dst[m][k] = *reinterpret_cast<const bf16x8*>((char*)SA(b, h) + lds_byte(wr * 64 + m * 16 + fr, k * 32 + fq * 8))
; #define LDB(dst, b, h) for (int n = 0; n < 2; ++n) for (int k = 0; k < 2; ++k) \
;     dst[n][k] = *reinterpret_cast<const bf16x8*>((char*)SB(b, h) + lds_byte(wc * 32 + n * 16 + fr, k * 32 + fq * 8))
; #define MMA(ai, bj, At, Bt_) do { __builtin_amdgcn_s_setprio(1); \
;     for (int m = 0; m < 4; ++m) for (int n = 0; n < 2; ++n) for (int k = 0; k < 2; ++k) \
;       acc[ai][bj][m][n] = __builtin_amdgcn_mfma_f32_16x16x32_bf16(At[m][k], Bt_[n][k], acc[ai][bj][m][n], 0, 0, 0); \
;     __builtin_amdgcn_s_setprio(0); } while (0)
; #define WAIT_L(n) asm volatile("s_waitcnt lgkmcnt(" #n ")" ::: "memory")
; #define BAR __builtin_amdgcn_s_barrier()
; #define SCHED __builtin_amdgcn_sched_barrier(0)
;     ...
;       LDB(B0, 0, 0); SCHED; LDA(At, 0, 0); STAGE(SA(1, 1), A, brow + HALF, t + 1);
;       WAIT_L(8); BAR; WAIT_L(0); MMA(0, 0, At, B0); BAR; SCHED;
;       LDB(B1, 0, 1); STAGE(SB(0, 0), Bt, bcol, t + 2);
;       BAR; WAIT_L(0); MMA(0, 1, At, B1); BAR;
;       LDA(At, 0, 1); STAGE(SA(0, 0), A, brow, t + 2);
;       BAR; WAIT_L(0); MMA(1, 0, At, B0); BAR; SCHED;
.LBB0_202:
	v_add_u32_e32 v143, s2, v142
	ds_read_b128 v[146:149], v143
	ds_read_b128 v[150:153], v143 offset:1024
	ds_read_b128 v[154:157], v143 offset:2048
	ds_read_b128 v[158:161], v143 offset:3072
	s_add_u32 s66, s50, s16
	s_addc_u32 s67, s51, s17
	s_add_i32 s58, s21, 0xc000
	ds_read_b128 v[162:165], v133
	ds_read_b128 v[184:187], v133 offset:1024
	ds_read_b128 v[188:191], v134
	ds_read_b128 v[192:195], v134 offset:1024
	ds_read_b128 v[196:199], v137
	ds_read_b128 v[200:203], v137 offset:1024
	ds_read_b128 v[204:207], v139
	ds_read_b128 v[208:211], v139 offset:1024
	s_mov_b32 m0, s58
	v_lshl_add_u64 v[144:145], s[66:67], 0, v[0:1]
	s_add_i32 s57, s21, 0xe000
	global_load_lds_dwordx4 v[144:145], off
	v_lshl_add_u64 v[144:145], s[66:67], 0, v[140:141]
	s_mov_b32 m0, s57
	s_nop 0
	global_load_lds_dwordx4 v[144:145], off
	s_waitcnt lgkmcnt(8)
	s_barrier
	s_waitcnt lgkmcnt(0)
	v_mfma_f32_16x16x32_bf16 v[126:129], v[162:165], v[146:149], v[126:129]
	v_mfma_f32_16x16x32_bf16 v[122:125], v[162:165], v[154:157], v[122:125]
	v_mfma_f32_16x16x32_bf16 v[118:121], v[188:191], v[146:149], v[118:121]
	v_mfma_f32_16x16x32_bf16 v[114:117], v[188:191], v[154:157], v[114:117]
	v_mfma_f32_16x16x32_bf16 v[110:113], v[196:199], v[146:149], v[110:113]
	v_mfma_f32_16x16x32_bf16 v[106:109], v[196:199], v[154:157], v[106:109]
	v_mfma_f32_16x16x32_bf16 v[102:105], v[204:207], v[146:149], v[102:105]
	v_mfma_f32_16x16x32_bf16 v[98:101], v[204:207], v[154:157], v[98:101]
	v_mfma_f32_16x16x32_bf16 v[126:129], v[184:187], v[150:153], v[126:129]
	v_mfma_f32_16x16x32_bf16 v[122:125], v[184:187], v[158:161], v[122:125]
	v_mfma_f32_16x16x32_bf16 v[118:121], v[192:195], v[150:153], v[118:121]
	v_mfma_f32_16x16x32_bf16 v[114:117], v[192:195], v[158:161], v[114:117]
	v_mfma_f32_16x16x32_bf16 v[110:113], v[200:203], v[150:153], v[110:113]
	v_mfma_f32_16x16x32_bf16 v[106:109], v[200:203], v[158:161], v[106:109]
	v_mfma_f32_16x16x32_bf16 v[102:105], v[208:211], v[150:153], v[102:105]
	v_mfma_f32_16x16x32_bf16 v[98:101], v[208:211], v[158:161], v[98:101]
	s_barrier
	s_add_i32 s55, s55, 2
	s_add_u32 s59, s11, s16
	s_addc_u32 s63, s44, s17
	s_add_u32 s66, s59, 0x100
	v_add_u32_e32 v144, s76, v142
	s_addc_u32 s67, s63, 0
	s_mov_b32 m0, s29
	ds_read_b128 v[212:215], v144
	ds_read_b128 v[216:219], v144 offset:1024
	ds_read_b128 v[220:223], v144 offset:2048
	ds_read_b128 v[224:227], v144 offset:3072
	s_nop 0
	v_lshl_add_u64 v[166:167], s[66:67], 0, v[0:1]
	global_load_lds_dwordx4 v[166:167], off
	v_lshl_add_u64 v[166:167], s[66:67], 0, v[140:141]
	s_mov_b32 m0, s30
	s_nop 0
	global_load_lds_dwordx4 v[166:167], off
	s_barrier
	s_waitcnt lgkmcnt(0)
	v_mfma_f32_16x16x32_bf16 v[94:97], v[162:165], v[212:215], v[94:97]
	v_mfma_f32_16x16x32_bf16 v[90:93], v[162:165], v[220:223], v[90:93]
	v_mfma_f32_16x16x32_bf16 v[86:89], v[188:191], v[212:215], v[86:89]
	v_mfma_f32_16x16x32_bf16 v[82:85], v[188:191], v[220:223], v[82:85]
	v_mfma_f32_16x16x32_bf16 v[78:81], v[196:199], v[212:215], v[78:81]
	v_mfma_f32_16x16x32_bf16 v[74:77], v[196:199], v[220:223], v[74:77]
	v_mfma_f32_16x16x32_bf16 v[70:73], v[204:207], v[212:215], v[70:73]
	v_mfma_f32_16x16x32_bf16 v[66:69], v[204:207], v[220:223], v[66:69]
	v_mfma_f32_16x16x32_bf16 v[94:97], v[184:187], v[216:219], v[94:97]
	v_mfma_f32_16x16x32_bf16 v[90:93], v[184:187], v[224:227], v[90:93]
	v_mfma_f32_16x16x32_bf16 v[86:89], v[192:195], v[216:219], v[86:89]
	v_mfma_f32_16x16x32_bf16 v[82:85], v[192:195], v[224:227], v[82:85]
	v_mfma_f32_16x16x32_bf16 v[78:81], v[200:203], v[216:219], v[78:81]
	v_mfma_f32_16x16x32_bf16 v[74:77], v[200:203], v[224:227], v[74:77]
	v_mfma_f32_16x16x32_bf16 v[70:73], v[208:211], v[216:219], v[70:73]
	v_mfma_f32_16x16x32_bf16 v[66:69], v[208:211], v[224:227], v[66:69]
	s_add_u32 s65, s13, s16
	s_addc_u32 s70, s45, s17
	s_add_u32 s66, s65, 0x100
	s_addc_u32 s67, s70, 0
	s_mov_b32 m0, s21
	s_barrier
	ds_read_b128 v[162:165], v133 offset:16384
	ds_read_b128 v[184:187], v133 offset:17408
	ds_read_b128 v[188:191], v134 offset:16384
	ds_read_b128 v[192:195], v134 offset:17408
	ds_read_b128 v[196:199], v137 offset:16384
	ds_read_b128 v[200:203], v137 offset:17408
	ds_read_b128 v[204:207], v139 offset:16384
	ds_read_b128 v[208:211], v139 offset:17408
	s_nop 0
	v_lshl_add_u64 v[166:167], s[66:67], 0, v[0:1]
	global_load_lds_dwordx4 v[166:167], off
	v_lshl_add_u64 v[166:167], s[66:67], 0, v[140:141]
	s_mov_b32 m0, s31
	s_nop 0
	global_load_lds_dwordx4 v[166:167], off
	s_barrier
	s_waitcnt lgkmcnt(0)
	v_mfma_f32_16x16x32_bf16 v[62:65], v[162:165], v[146:149], v[62:65]
	v_mfma_f32_16x16x32_bf16 v[58:61], v[162:165], v[154:157], v[58:61]
	v_mfma_f32_16x16x32_bf16 v[54:57], v[188:191], v[146:149], v[54:57]
	v_mfma_f32_16x16x32_bf16 v[50:53], v[188:191], v[154:157], v[50:53]
	v_mfma_f32_16x16x32_bf16 v[46:49], v[196:199], v[146:149], v[46:49]
	v_mfma_f32_16x16x32_bf16 v[42:45], v[196:199], v[154:157], v[42:45]
	v_mfma_f32_16x16x32_bf16 v[38:41], v[204:207], v[146:149], v[38:41]
	v_mfma_f32_16x16x32_bf16 v[34:37], v[204:207], v[154:157], v[34:37]
	v_mfma_f32_16x16x32_bf16 v[62:65], v[184:187], v[150:153], v[62:65]
	v_mfma_f32_16x16x32_bf16 v[58:61], v[184:187], v[158:161], v[58:61]
	v_mfma_f32_16x16x32_bf16 v[54:57], v[192:195], v[150:153], v[54:57]
	v_mfma_f32_16x16x32_bf16 v[50:53], v[192:195], v[158:161], v[50:53]
	v_mfma_f32_16x16x32_bf16 v[46:49], v[200:203], v[150:153], v[46:49]
	v_mfma_f32_16x16x32_bf16 v[42:45], v[200:203], v[158:161], v[42:45]
	v_mfma_f32_16x16x32_bf16 v[38:41], v[208:211], v[150:153], v[38:41]
	v_mfma_f32_16x16x32_bf16 v[34:37], v[208:211], v[158:161], v[34:37]
	s_barrier
; #define LDA(dst, b, h) for (int m = 0; m < 4; ++m) for (int k = 0; k < 2; ++k) \
;     dst[m][k] = *reinterpret_cast<const bf16x8*>((char*)SA(b, h) + lds_byte(wr * 64 + m * 16 + fr, k * 32 + fq * 8))
; #define LDB(dst, b, h) for (int n = 0; n < 2; ++n) for (int k = 0; k < 2; ++k) \
;     dst[n][k] = *reinterpret_cast<const bf16x8*>((char*)SB(b, h) + lds_byte(wc * 32 + n * 16 + fr, k * 32 + fq * 8))
; #define MMA(ai, bj, At, Bt_) do { __builtin_amdgcn_s_setprio(1); \
;     for (int m = 0; m < 4; ++m) for (int n = 0; n < 2; ++n) for (int k = 0; k < 2; ++k) \
;       acc[ai][bj][m][n] = __builtin_amdgcn_mfma_f32_16x16x32_bf16(At[m][k], Bt_[n][k], acc[ai][bj][m][n], 0, 0, 0); \
;     __builtin_amdgcn_s_setprio(0); } while (0)
; #define WAIT_V(n) asm volatile("s_waitcnt vmcnt(" #n ")" ::: "memory")
; #define WAIT_L(n) asm volatile("s_waitcnt lgkmcnt(" #n ")" ::: "memory")
; #define BAR __builtin_amdgcn_s_barrier()
; #define SCHED __builtin_amdgcn_sched_barrier(0)
;     ...
;       STAGE(SB(0, 1), Bt, bcol + HALF, t + 2);
;       WAIT_V(6); BAR; MMA(1, 1, At, B1); BAR;
;       LDB(B0, 1, 0); SCHED; LDA(At, 1, 0); STAGE(SA(0, 1), A, brow + HALF, t + 2);
;       WAIT_L(8); BAR; WAIT_L(0); MMA(0, 0, At, B0); BAR; SCHED;
;       LDB(B1, 1, 1); STAGE(SB(1, 0), Bt, bcol, t + 3);
;       BAR; WAIT_L(0); MMA(0, 1, At, B1); BAR;
;       LDA(At, 1, 1); STAGE(SA(1, 0), A, brow, t + 3);
	s_add_u32 s66, s59, 0x80100
	s_addc_u32 s67, s63, 0
	s_mov_b32 m0, s34
	s_nop 0
	v_lshl_add_u64 v[146:147], s[66:67], 0, v[0:1]
	global_load_lds_dwordx4 v[146:147], off
	v_lshl_add_u64 v[146:147], s[66:67], 0, v[140:141]
	s_mov_b32 m0, s35
	s_nop 0
	global_load_lds_dwordx4 v[146:147], off
	s_waitcnt vmcnt(6)
	s_barrier
	v_mfma_f32_16x16x32_bf16 v[30:33], v[162:165], v[212:215], v[30:33]
	v_mfma_f32_16x16x32_bf16 v[26:29], v[162:165], v[220:223], v[26:29]
	v_mfma_f32_16x16x32_bf16 v[22:25], v[188:191], v[212:215], v[22:25]
	v_mfma_f32_16x16x32_bf16 v[18:21], v[188:191], v[220:223], v[18:21]
	v_mfma_f32_16x16x32_bf16 v[14:17], v[196:199], v[212:215], v[14:17]
	v_mfma_f32_16x16x32_bf16 v[10:13], v[196:199], v[220:223], v[10:13]
	v_mfma_f32_16x16x32_bf16 v[6:9], v[204:207], v[212:215], v[6:9]
	v_mfma_f32_16x16x32_bf16 v[2:5], v[204:207], v[220:223], v[2:5]
	v_mfma_f32_16x16x32_bf16 v[30:33], v[184:187], v[216:219], v[30:33]
	v_mfma_f32_16x16x32_bf16 v[26:29], v[184:187], v[224:227], v[26:29]
	v_mfma_f32_16x16x32_bf16 v[22:25], v[192:195], v[216:219], v[22:25]
	v_mfma_f32_16x16x32_bf16 v[18:21], v[192:195], v[224:227], v[18:21]
	v_mfma_f32_16x16x32_bf16 v[14:17], v[200:203], v[216:219], v[14:17]
	v_mfma_f32_16x16x32_bf16 v[10:13], v[200:203], v[224:227], v[10:13]
	v_mfma_f32_16x16x32_bf16 v[6:9], v[208:211], v[216:219], v[6:9]
	v_mfma_f32_16x16x32_bf16 v[2:5], v[208:211], v[224:227], v[2:5]
	v_add_u32_e32 v145, s77, v142
	s_barrier
	ds_read_b128 v[148:151], v145
	ds_read_b128 v[152:155], v145 offset:1024
	ds_read_b128 v[156:159], v145 offset:2048
	ds_read_b128 v[160:163], v145 offset:3072
	s_add_u32 s66, s65, 0x80100
	s_addc_u32 s67, s70, 0
	s_mov_b32 m0, s37
	ds_read_b128 v[164:167], v133 offset:32768
	ds_read_b128 v[184:187], v133 offset:33792
	ds_read_b128 v[188:191], v134 offset:32768
	ds_read_b128 v[192:195], v134 offset:33792
	ds_read_b128 v[196:199], v137 offset:32768
	ds_read_b128 v[200:203], v137 offset:33792
	ds_read_b128 v[204:207], v139 offset:32768
	ds_read_b128 v[208:211], v139 offset:33792
	s_nop 0
	v_lshl_add_u64 v[146:147], s[66:67], 0, v[0:1]
	global_load_lds_dwordx4 v[146:147], off
	v_lshl_add_u64 v[146:147], s[66:67], 0, v[140:141]
	s_mov_b32 m0, s38
	s_nop 0
	global_load_lds_dwordx4 v[146:147], off
	s_waitcnt lgkmcnt(8)
	s_barrier
	s_waitcnt lgkmcnt(0)
	v_mfma_f32_16x16x32_bf16 v[126:129], v[164:167], v[148:151], v[126:129]
	v_mfma_f32_16x16x32_bf16 v[122:125], v[164:167], v[156:159], v[122:125]
	v_mfma_f32_16x16x32_bf16 v[118:121], v[188:191], v[148:151], v[118:121]
	v_mfma_f32_16x16x32_bf16 v[114:117], v[188:191], v[156:159], v[114:117]
	v_mfma_f32_16x16x32_bf16 v[110:113], v[196:199], v[148:151], v[110:113]
	v_mfma_f32_16x16x32_bf16 v[106:109], v[196:199], v[156:159], v[106:109]
	v_mfma_f32_16x16x32_bf16 v[102:105], v[204:207], v[148:151], v[102:105]
	v_mfma_f32_16x16x32_bf16 v[98:101], v[204:207], v[156:159], v[98:101]
	v_mfma_f32_16x16x32_bf16 v[126:129], v[184:187], v[152:155], v[126:129]
	v_mfma_f32_16x16x32_bf16 v[122:125], v[184:187], v[160:163], v[122:125]
	v_mfma_f32_16x16x32_bf16 v[118:121], v[192:195], v[152:155], v[118:121]
	v_mfma_f32_16x16x32_bf16 v[114:117], v[192:195], v[160:163], v[114:117]
	v_mfma_f32_16x16x32_bf16 v[110:113], v[200:203], v[152:155], v[110:113]
	v_mfma_f32_16x16x32_bf16 v[106:109], v[200:203], v[160:163], v[106:109]
	v_mfma_f32_16x16x32_bf16 v[102:105], v[208:211], v[152:155], v[102:105]
	v_mfma_f32_16x16x32_bf16 v[98:101], v[208:211], v[160:163], v[98:101]
	s_barrier
	s_add_u32 s66, s59, 0x180
	v_add_u32_e32 v146, s78, v142
	s_addc_u32 s67, s63, 0
	s_mov_b32 m0, s39
	ds_read_b128 v[212:215], v146
	ds_read_b128 v[216:219], v146 offset:1024
	ds_read_b128 v[220:223], v146 offset:2048
	ds_read_b128 v[224:227], v146 offset:3072
	s_nop 0
	v_lshl_add_u64 v[228:229], s[66:67], 0, v[0:1]
	global_load_lds_dwordx4 v[228:229], off
	v_lshl_add_u64 v[228:229], s[66:67], 0, v[140:141]
	s_mov_b32 m0, s40
	s_nop 0
	global_load_lds_dwordx4 v[228:229], off
	s_barrier
	s_waitcnt lgkmcnt(0)
	v_mfma_f32_16x16x32_bf16 v[94:97], v[164:167], v[212:215], v[94:97]
	v_mfma_f32_16x16x32_bf16 v[90:93], v[164:167], v[220:223], v[90:93]
	v_mfma_f32_16x16x32_bf16 v[86:89], v[188:191], v[212:215], v[86:89]
	v_mfma_f32_16x16x32_bf16 v[82:85], v[188:191], v[220:223], v[82:85]
	v_mfma_f32_16x16x32_bf16 v[78:81], v[196:199], v[212:215], v[78:81]
	v_mfma_f32_16x16x32_bf16 v[74:77], v[196:199], v[220:223], v[74:77]
	v_mfma_f32_16x16x32_bf16 v[70:73], v[204:207], v[212:215], v[70:73]
	v_mfma_f32_16x16x32_bf16 v[66:69], v[204:207], v[220:223], v[66:69]
	v_mfma_f32_16x16x32_bf16 v[94:97], v[184:187], v[216:219], v[94:97]
	v_mfma_f32_16x16x32_bf16 v[90:93], v[184:187], v[224:227], v[90:93]
	v_mfma_f32_16x16x32_bf16 v[86:89], v[192:195], v[216:219], v[86:89]
	v_mfma_f32_16x16x32_bf16 v[82:85], v[192:195], v[224:227], v[82:85]
	v_mfma_f32_16x16x32_bf16 v[78:81], v[200:203], v[216:219], v[78:81]
	v_mfma_f32_16x16x32_bf16 v[74:77], v[200:203], v[224:227], v[74:77]
	v_mfma_f32_16x16x32_bf16 v[70:73], v[208:211], v[216:219], v[70:73]
	v_mfma_f32_16x16x32_bf16 v[66:69], v[208:211], v[224:227], v[66:69]
	s_add_u32 s66, s65, 0x180
	s_addc_u32 s67, s70, 0
	s_mov_b32 m0, s41
	s_barrier
	ds_read_b128 v[164:167], v133 offset:49152
	ds_read_b128 v[184:187], v133 offset:50176
	ds_read_b128 v[188:191], v134 offset:49152
	ds_read_b128 v[192:195], v134 offset:50176
	ds_read_b128 v[196:199], v137 offset:49152
	ds_read_b128 v[200:203], v137 offset:50176
	ds_read_b128 v[204:207], v139 offset:49152
	ds_read_b128 v[208:211], v139 offset:50176
	s_nop 0
	v_lshl_add_u64 v[228:229], s[66:67], 0, v[0:1]
	global_load_lds_dwordx4 v[228:229], off
	v_lshl_add_u64 v[228:229], s[66:67], 0, v[140:141]
	s_mov_b32 m0, s42
	s_nop 0
	global_load_lds_dwordx4 v[228:229], off
	s_barrier
; #define LDA(dst, b, h) for (int m = 0; m < 4; ++m) for (int k = 0; k < 2; ++k) \
;     dst[m][k] = *reinterpret_cast<const bf16x8*>((char*)SA(b, h) + lds_byte(wr * 64 + m * 16 + fr, k * 32 + fq * 8))
; #define LDB(dst, b, h) for (int n = 0; n < 2; ++n) for (int k = 0; k < 2; ++k) \
;     dst[n][k] = *reinterpret_cast<const bf16x8*>((char*)SB(b, h) + lds_byte(wc * 32 + n * 16 + fr, k * 32 + fq * 8))
; #define MMA(ai, bj, At, Bt_) do { __builtin_amdgcn_s_setprio(1); \
;     for (int m = 0; m < 4; ++m) for (int n = 0; n < 2; ++n) for (int k = 0; k < 2; ++k) \
;       acc[ai][bj][m][n] = __builtin_amdgcn_mfma_f32_16x16x32_bf16(At[m][k], Bt_[n][k], acc[ai][bj][m][n], 0, 0, 0); \
;     __builtin_amdgcn_s_setprio(0); } while (0)
; #define WAIT_V(n) asm volatile("s_waitcnt vmcnt(" #n ")" ::: "memory")
; #define WAIT_L(n) asm volatile("s_waitcnt lgkmcnt(" #n ")" ::: "memory")
; #define BAR __builtin_amdgcn_s_barrier()
; #define SCHED __builtin_amdgcn_sched_barrier(0)
;     ...
;       BAR; WAIT_L(0); MMA(1, 0, At, B0); BAR; SCHED;
;       STAGE(SB(1, 1), Bt, bcol + HALF, t + 3);
;       WAIT_V(6); BAR; MMA(1, 1, At, B1); BAR;
;     }
;     { LDB(B0, 0, 0); LDA(At, 0, 0); STAGE(SA(1, 1), A, brow + HALF, nt - 1);
;       BAR; WAIT_L(0); MMA(0, 0, At, B0); BAR;
	s_waitcnt lgkmcnt(0)
	v_mfma_f32_16x16x32_bf16 v[62:65], v[164:167], v[148:151], v[62:65]
	v_mfma_f32_16x16x32_bf16 v[58:61], v[164:167], v[156:159], v[58:61]
	v_mfma_f32_16x16x32_bf16 v[54:57], v[188:191], v[148:151], v[54:57]
	v_mfma_f32_16x16x32_bf16 v[50:53], v[188:191], v[156:159], v[50:53]
	v_mfma_f32_16x16x32_bf16 v[46:49], v[196:199], v[148:151], v[46:49]
	v_mfma_f32_16x16x32_bf16 v[42:45], v[196:199], v[156:159], v[42:45]
	v_mfma_f32_16x16x32_bf16 v[38:41], v[204:207], v[148:151], v[38:41]
	v_mfma_f32_16x16x32_bf16 v[34:37], v[204:207], v[156:159], v[34:37]
	v_mfma_f32_16x16x32_bf16 v[62:65], v[184:187], v[152:155], v[62:65]
	v_mfma_f32_16x16x32_bf16 v[58:61], v[184:187], v[160:163], v[58:61]
	v_mfma_f32_16x16x32_bf16 v[54:57], v[192:195], v[152:155], v[54:57]
	v_mfma_f32_16x16x32_bf16 v[50:53], v[192:195], v[160:163], v[50:53]
	v_mfma_f32_16x16x32_bf16 v[46:49], v[200:203], v[152:155], v[46:49]
	v_mfma_f32_16x16x32_bf16 v[42:45], v[200:203], v[160:163], v[42:45]
	v_mfma_f32_16x16x32_bf16 v[38:41], v[208:211], v[152:155], v[38:41]
	v_mfma_f32_16x16x32_bf16 v[34:37], v[208:211], v[160:163], v[34:37]
	s_barrier
	s_add_u32 s66, s59, 0x80180
	s_addc_u32 s67, s63, 0
	s_mov_b32 m0, s18
	s_nop 0
	v_lshl_add_u64 v[148:149], s[66:67], 0, v[0:1]
	global_load_lds_dwordx4 v[148:149], off
	v_lshl_add_u64 v[148:149], s[66:67], 0, v[140:141]
	s_mov_b32 m0, s19
	s_nop 0
	global_load_lds_dwordx4 v[148:149], off
	s_waitcnt vmcnt(6)
	s_barrier
	v_mfma_f32_16x16x32_bf16 v[30:33], v[164:167], v[212:215], v[30:33]
	v_mfma_f32_16x16x32_bf16 v[26:29], v[164:167], v[220:223], v[26:29]
	v_mfma_f32_16x16x32_bf16 v[22:25], v[188:191], v[212:215], v[22:25]
	v_mfma_f32_16x16x32_bf16 v[18:21], v[188:191], v[220:223], v[18:21]
	v_mfma_f32_16x16x32_bf16 v[14:17], v[196:199], v[212:215], v[14:17]
	v_mfma_f32_16x16x32_bf16 v[10:13], v[196:199], v[220:223], v[10:13]
	v_mfma_f32_16x16x32_bf16 v[6:9], v[204:207], v[212:215], v[6:9]
	v_mfma_f32_16x16x32_bf16 v[2:5], v[204:207], v[220:223], v[2:5]
	v_mfma_f32_16x16x32_bf16 v[30:33], v[184:187], v[216:219], v[30:33]
	v_mfma_f32_16x16x32_bf16 v[26:29], v[184:187], v[224:227], v[26:29]
	v_mfma_f32_16x16x32_bf16 v[22:25], v[192:195], v[216:219], v[22:25]
	v_mfma_f32_16x16x32_bf16 v[18:21], v[192:195], v[224:227], v[18:21]
	v_mfma_f32_16x16x32_bf16 v[14:17], v[200:203], v[216:219], v[14:17]
	v_mfma_f32_16x16x32_bf16 v[10:13], v[200:203], v[224:227], v[10:13]
	v_mfma_f32_16x16x32_bf16 v[6:9], v[208:211], v[216:219], v[6:9]
	v_mfma_f32_16x16x32_bf16 v[2:5], v[208:211], v[224:227], v[2:5]
	s_add_u32 s11, s11, 0x100
	s_addc_u32 s44, s44, 0
	s_add_u32 s13, s13, 0x100
	s_addc_u32 s45, s45, 0
	s_add_u32 s50, s50, 0x100
	s_addc_u32 s51, s51, 0
	s_cmp_ge_u32 s55, s43
	s_barrier
	s_cbranch_scc0 .LBB0_202
	s_add_i32 s11, s48, s20
	s_add_i32 s48, s11, -1
	s_lshl_b64 s[16:17], s[48:49], 7
	s_add_u32 s11, s74, s16
	s_addc_u32 s13, s75, s17
	s_add_u32 s4, s11, s4
	s_addc_u32 s5, s13, s5
	s_mov_b32 m0, s58
	ds_read_b128 v[148:151], v143
	ds_read_b128 v[152:155], v143 offset:1024
	ds_read_b128 v[156:159], v143 offset:2048
	ds_read_b128 v[160:163], v143 offset:3072
	ds_read_b128 v[164:167], v133
	ds_read_b128 v[184:187], v133 offset:1024
	ds_read_b128 v[188:191], v134
	ds_read_b128 v[192:195], v134 offset:1024
	ds_read_b128 v[196:199], v137
	ds_read_b128 v[200:203], v137 offset:1024
	ds_read_b128 v[204:207], v139
	ds_read_b128 v[208:211], v139 offset:1024
	s_nop 0
	v_lshl_add_u64 v[142:143], s[4:5], 0, v[0:1]
	global_load_lds_dwordx4 v[142:143], off
	v_lshl_add_u64 v[140:141], s[4:5], 0, v[140:141]
	s_mov_b32 m0, s57
	s_nop 0
	global_load_lds_dwordx4 v[140:141], off
	s_barrier
	s_waitcnt lgkmcnt(0)
	s_setprio 1
	s_waitcnt lgkmcnt(0)
	v_mfma_f32_16x16x32_bf16 v[126:129], v[164:167], v[148:151], v[126:129]
	v_mfma_f32_16x16x32_bf16 v[122:125], v[164:167], v[156:159], v[122:125]
	v_mfma_f32_16x16x32_bf16 v[118:121], v[188:191], v[148:151], v[118:121]
	v_mfma_f32_16x16x32_bf16 v[110:113], v[196:199], v[148:151], v[110:113]
	v_mfma_f32_16x16x32_bf16 v[106:109], v[196:199], v[156:159], v[106:109]
	v_mfma_f32_16x16x32_bf16 v[102:105], v[204:207], v[148:151], v[102:105]
	v_mfma_f32_16x16x32_bf16 v[98:101], v[204:207], v[156:159], v[98:101]
	v_mfma_f32_16x16x32_bf16 v[126:129], v[184:187], v[152:155], v[126:129]
	v_mfma_f32_16x16x32_bf16 v[122:125], v[184:187], v[160:163], v[122:125]
	v_mfma_f32_16x16x32_bf16 v[118:121], v[192:195], v[152:155], v[118:121]
	v_mfma_f32_16x16x32_bf16 v[114:117], v[188:191], v[156:159], v[114:117]
	v_mfma_f32_16x16x32_bf16 v[110:113], v[200:203], v[152:155], v[110:113]
	v_mfma_f32_16x16x32_bf16 v[106:109], v[200:203], v[160:163], v[106:109]
	v_mfma_f32_16x16x32_bf16 v[102:105], v[208:211], v[152:155], v[102:105]
	v_mfma_f32_16x16x32_bf16 v[98:101], v[208:211], v[160:163], v[98:101]
	v_mfma_f32_16x16x32_bf16 v[140:143], v[192:195], v[160:163], v[114:117]
	s_setprio 0
	s_barrier
	s_nop 0
	ds_read_b128 v[114:117], v144
	ds_read_b128 v[212:215], v144 offset:1024
	ds_read_b128 v[216:219], v144 offset:2048
	ds_read_b128 v[220:223], v144 offset:3072
	s_barrier
; #define LDA(dst, b, h) for (int m = 0; m < 4; ++m) for (int k = 0; k < 2; ++k) \
;     dst[m][k] = *reinterpret_cast<const bf16x8*>((char*)SA(b, h) + lds_byte(wr * 64 + m * 16 + fr, k * 32 + fq * 8))
; #define LDB(dst, b, h) for (int n = 0; n < 2; ++n) for (int k = 0; k < 2; ++k) \
;     dst[n][k] = *reinterpret_cast<const bf16x8*>((char*)SB(b, h) + lds_byte(wc * 32 + n * 16 + fr, k * 32 + fq * 8))
; #define MMA(ai, bj, At, Bt_) do { __builtin_amdgcn_s_setprio(1); \
;     for (int m = 0; m < 4; ++m) for (int n = 0; n < 2; ++n) for (int k = 0; k < 2; ++k) \
;       acc[ai][bj][m][n] = __builtin_amdgcn_mfma_f32_16x16x32_bf16(At[m][k], Bt_[n][k], acc[ai][bj][m][n], 0, 0, 0); \
;     __builtin_amdgcn_s_setprio(0); } while (0)
; #define WAIT_V(n) asm volatile("s_waitcnt vmcnt(" #n ")" ::: "memory")
; #define WAIT_L(n) asm volatile("s_waitcnt lgkmcnt(" #n ")" ::: "memory")
; #define BAR __builtin_amdgcn_s_barrier()
;     ...
;       LDB(B1, 0, 1); BAR; WAIT_L(0); MMA(0, 1, At, B1); BAR;
;       LDA(At, 0, 1); WAIT_V(4); BAR; WAIT_L(0); MMA(1, 0, At, B0); MMA(1, 1, At, B1); BAR; }
;     { LDB(B0, 1, 0); LDA(At, 1, 0); WAIT_V(2); BAR; WAIT_L(0); MMA(0, 0, At, B0); BAR;
	s_waitcnt lgkmcnt(0)
	s_setprio 1
	s_waitcnt lgkmcnt(0)
	v_mfma_f32_16x16x32_bf16 v[90:93], v[164:167], v[216:219], v[90:93]
	v_mfma_f32_16x16x32_bf16 v[86:89], v[188:191], v[114:117], v[86:89]
	v_mfma_f32_16x16x32_bf16 v[94:97], v[164:167], v[114:117], v[94:97]
	v_mfma_f32_16x16x32_bf16 v[90:93], v[184:187], v[220:223], v[90:93]
	v_mfma_f32_16x16x32_bf16 v[86:89], v[192:195], v[212:215], v[86:89]
	v_mfma_f32_16x16x32_bf16 v[82:85], v[188:191], v[216:219], v[82:85]
	v_mfma_f32_16x16x32_bf16 v[78:81], v[196:199], v[114:117], v[78:81]
	v_mfma_f32_16x16x32_bf16 v[74:77], v[196:199], v[216:219], v[74:77]
	v_mfma_f32_16x16x32_bf16 v[70:73], v[204:207], v[114:117], v[70:73]
	v_mfma_f32_16x16x32_bf16 v[66:69], v[204:207], v[216:219], v[66:69]
	v_mfma_f32_16x16x32_bf16 v[224:227], v[184:187], v[212:215], v[94:97]
	v_mfma_f32_16x16x32_bf16 v[164:167], v[192:195], v[220:223], v[82:85]
	v_mfma_f32_16x16x32_bf16 v[184:187], v[200:203], v[212:215], v[78:81]
	v_mfma_f32_16x16x32_bf16 v[188:191], v[200:203], v[220:223], v[74:77]
	v_mfma_f32_16x16x32_bf16 v[192:195], v[208:211], v[212:215], v[70:73]
	v_mfma_f32_16x16x32_bf16 v[196:199], v[208:211], v[220:223], v[66:69]
	s_setprio 0
	s_barrier
	s_nop 0
	ds_read_b128 v[66:69], v133 offset:16384
	ds_read_b128 v[70:73], v133 offset:17408
	ds_read_b128 v[74:77], v134 offset:16384
	ds_read_b128 v[78:81], v134 offset:17408
	ds_read_b128 v[82:85], v137 offset:16384
	ds_read_b128 v[94:97], v137 offset:17408
	ds_read_b128 v[200:203], v139 offset:16384
	ds_read_b128 v[204:207], v139 offset:17408
	s_waitcnt vmcnt(4)
	s_barrier
	s_waitcnt lgkmcnt(0)
	s_setprio 1
	s_waitcnt lgkmcnt(0)
	v_mfma_f32_16x16x32_bf16 v[62:65], v[66:69], v[148:151], v[62:65]
	v_mfma_f32_16x16x32_bf16 v[58:61], v[66:69], v[156:159], v[58:61]
	v_mfma_f32_16x16x32_bf16 v[54:57], v[74:77], v[148:151], v[54:57]
	v_mfma_f32_16x16x32_bf16 v[50:53], v[74:77], v[156:159], v[50:53]
	v_mfma_f32_16x16x32_bf16 v[46:49], v[82:85], v[148:151], v[46:49]
	v_mfma_f32_16x16x32_bf16 v[42:45], v[82:85], v[156:159], v[42:45]
	v_mfma_f32_16x16x32_bf16 v[38:41], v[200:203], v[148:151], v[38:41]
	v_mfma_f32_16x16x32_bf16 v[34:37], v[200:203], v[156:159], v[34:37]
	v_mfma_f32_16x16x32_bf16 v[62:65], v[70:73], v[152:155], v[62:65]
	v_mfma_f32_16x16x32_bf16 v[58:61], v[70:73], v[160:163], v[58:61]
	v_mfma_f32_16x16x32_bf16 v[54:57], v[78:81], v[152:155], v[54:57]
	v_mfma_f32_16x16x32_bf16 v[50:53], v[78:81], v[160:163], v[50:53]
	v_mfma_f32_16x16x32_bf16 v[46:49], v[94:97], v[152:155], v[46:49]
	v_mfma_f32_16x16x32_bf16 v[42:45], v[94:97], v[160:163], v[42:45]
	v_mfma_f32_16x16x32_bf16 v[38:41], v[204:207], v[152:155], v[38:41]
	v_mfma_f32_16x16x32_bf16 v[34:37], v[204:207], v[160:163], v[34:37]
	s_setprio 0
	s_setprio 1
	v_mfma_f32_16x16x32_bf16 v[30:33], v[66:69], v[114:117], v[30:33]
	v_mfma_f32_16x16x32_bf16 v[26:29], v[66:69], v[216:219], v[26:29]
	v_mfma_f32_16x16x32_bf16 v[22:25], v[74:77], v[114:117], v[22:25]
	v_mfma_f32_16x16x32_bf16 v[18:21], v[74:77], v[216:219], v[18:21]
	v_mfma_f32_16x16x32_bf16 v[14:17], v[82:85], v[114:117], v[14:17]
	v_mfma_f32_16x16x32_bf16 v[10:13], v[82:85], v[216:219], v[10:13]
	v_mfma_f32_16x16x32_bf16 v[6:9], v[200:203], v[114:117], v[6:9]
	v_mfma_f32_16x16x32_bf16 v[2:5], v[200:203], v[216:219], v[2:5]
	v_mfma_f32_16x16x32_bf16 v[148:151], v[70:73], v[212:215], v[30:33]
	v_mfma_f32_16x16x32_bf16 v[152:155], v[70:73], v[220:223], v[26:29]
	v_mfma_f32_16x16x32_bf16 v[156:159], v[78:81], v[212:215], v[22:25]
	v_mfma_f32_16x16x32_bf16 v[160:163], v[78:81], v[220:223], v[18:21]
	v_mfma_f32_16x16x32_bf16 v[208:211], v[94:97], v[212:215], v[14:17]
	v_mfma_f32_16x16x32_bf16 v[228:231], v[94:97], v[220:223], v[10:13]
	v_mfma_f32_16x16x32_bf16 v[212:215], v[204:207], v[212:215], v[6:9]
	v_mfma_f32_16x16x32_bf16 v[200:203], v[204:207], v[220:223], v[2:5]
	s_setprio 0
	s_barrier
	ds_read_b128 v[14:17], v145
	ds_read_b128 v[30:33], v145 offset:1024
	ds_read_b128 v[204:207], v145 offset:2048
	ds_read_b128 v[216:219], v145 offset:3072
	ds_read_b128 v[2:5], v133 offset:32768
	ds_read_b128 v[6:9], v133 offset:33792
	ds_read_b128 v[10:13], v134 offset:32768
	ds_read_b128 v[18:21], v134 offset:33792
	ds_read_b128 v[22:25], v137 offset:32768
	ds_read_b128 v[26:29], v137 offset:33792
	ds_read_b128 v[220:223], v139 offset:32768
	ds_read_b128 v[232:235], v139 offset:33792
	s_waitcnt vmcnt(2)
	s_barrier
; #define LDA(dst, b, h) for (int m = 0; m < 4; ++m) for (int k = 0; k < 2; ++k) \
;     dst[m][k] = *reinterpret_cast<const bf16x8*>((char*)SA(b, h) + lds_byte(wr * 64 + m * 16 + fr, k * 32 + fq * 8))
; #define LDB(dst, b, h) for (int n = 0; n < 2; ++n) for (int k = 0; k < 2; ++k) \
;     dst[n][k] = *reinterpret_cast<const bf16x8*>((char*)SB(b, h) + lds_byte(wc * 32 + n * 16 + fr, k * 32 + fq * 8))
; #define MMA(ai, bj, At, Bt_) do { __builtin_amdgcn_s_setprio(1); \
;     for (int m = 0; m < 4; ++m) for (int n = 0; n < 2; ++n) for (int k = 0; k < 2; ++k) \
;       acc[ai][bj][m][n] = __builtin_amdgcn_mfma_f32_16x16x32_bf16(At[m][k], Bt_[n][k], acc[ai][bj][m][n], 0, 0, 0); \
;     __builtin_amdgcn_s_setprio(0); } while (0)
; #define WAIT_V(n) asm volatile("s_waitcnt vmcnt(" #n ")" ::: "memory")
; #define WAIT_L(n) asm volatile("s_waitcnt lgkmcnt(" #n ")" ::: "memory")
; #define BAR __builtin_amdgcn_s_barrier()
;     ...
;     { LDB(B0, 1, 0); LDA(At, 1, 0); WAIT_V(2); BAR; WAIT_L(0); MMA(0, 0, At, B0); BAR;
;       LDB(B1, 1, 1); WAIT_V(0); BAR; WAIT_L(0); MMA(0, 1, At, B1); BAR;
;       LDA(At, 1, 1); BAR; WAIT_L(0); MMA(1, 0, At, B0); MMA(1, 1, At, B1); BAR; }
;     if (wr == 0) BAR;
	s_waitcnt lgkmcnt(0)
	s_setprio 1
	s_waitcnt lgkmcnt(0)
	v_mfma_f32_16x16x32_bf16 v[66:69], v[2:5], v[14:17], v[126:129]
	v_mfma_f32_16x16x32_bf16 v[114:117], v[6:9], v[30:33], v[66:69]
	v_mfma_f32_16x16x32_bf16 v[66:69], v[2:5], v[204:207], v[122:125]
	v_mfma_f32_16x16x32_bf16 v[126:129], v[6:9], v[216:219], v[66:69]
	v_mfma_f32_16x16x32_bf16 v[66:69], v[10:13], v[14:17], v[118:121]
	v_mfma_f32_16x16x32_bf16 v[82:85], v[18:21], v[30:33], v[66:69]
	v_mfma_f32_16x16x32_bf16 v[66:69], v[10:13], v[204:207], v[140:143]
	v_mfma_f32_16x16x32_bf16 v[94:97], v[18:21], v[216:219], v[66:69]
	v_mfma_f32_16x16x32_bf16 v[66:69], v[22:25], v[14:17], v[110:113]
	v_mfma_f32_16x16x32_bf16 v[74:77], v[26:29], v[30:33], v[66:69]
	v_mfma_f32_16x16x32_bf16 v[66:69], v[22:25], v[204:207], v[106:109]
	v_mfma_f32_16x16x32_bf16 v[78:81], v[26:29], v[216:219], v[66:69]
	v_mfma_f32_16x16x32_bf16 v[66:69], v[220:223], v[14:17], v[102:105]
	v_mfma_f32_16x16x32_bf16 v[70:73], v[220:223], v[204:207], v[98:101]
	v_mfma_f32_16x16x32_bf16 v[66:69], v[232:235], v[30:33], v[66:69]
	v_mfma_f32_16x16x32_bf16 v[70:73], v[232:235], v[216:219], v[70:73]
	s_setprio 0
	s_barrier
	ds_read_b128 v[140:143], v146
	ds_read_b128 v[236:239], v146 offset:1024
	ds_read_b128 v[240:243], v146 offset:2048
	ds_read_b128 v[144:147], v146 offset:3072
	s_waitcnt vmcnt(0)
	s_barrier
	s_waitcnt lgkmcnt(0)
	s_setprio 1
	s_waitcnt lgkmcnt(0)
	v_mfma_f32_16x16x32_bf16 v[98:101], v[2:5], v[140:143], v[224:227]
	v_mfma_f32_16x16x32_bf16 v[2:5], v[2:5], v[240:243], v[90:93]
	v_mfma_f32_16x16x32_bf16 v[118:121], v[6:9], v[144:147], v[2:5]
	v_mfma_f32_16x16x32_bf16 v[2:5], v[10:13], v[140:143], v[86:89]
	v_mfma_f32_16x16x32_bf16 v[102:105], v[18:21], v[236:239], v[2:5]
	v_mfma_f32_16x16x32_bf16 v[2:5], v[10:13], v[240:243], v[164:167]
	v_mfma_f32_16x16x32_bf16 v[122:125], v[18:21], v[144:147], v[2:5]
	v_mfma_f32_16x16x32_bf16 v[2:5], v[22:25], v[140:143], v[184:187]
	v_mfma_f32_16x16x32_bf16 v[90:93], v[26:29], v[236:239], v[2:5]
	v_mfma_f32_16x16x32_bf16 v[2:5], v[22:25], v[240:243], v[188:191]
	v_mfma_f32_16x16x32_bf16 v[110:113], v[26:29], v[144:147], v[2:5]
	v_mfma_f32_16x16x32_bf16 v[2:5], v[220:223], v[140:143], v[192:195]
	v_mfma_f32_16x16x32_bf16 v[86:89], v[232:235], v[236:239], v[2:5]
	v_mfma_f32_16x16x32_bf16 v[2:5], v[220:223], v[240:243], v[196:199]
	v_mfma_f32_16x16x32_bf16 v[98:101], v[6:9], v[236:239], v[98:101]
	v_mfma_f32_16x16x32_bf16 v[106:109], v[232:235], v[144:147], v[2:5]
	s_setprio 0
	s_barrier
	ds_read_b128 v[164:167], v133 offset:49152
	ds_read_b128 v[184:187], v133 offset:50176
	ds_read_b128 v[188:191], v134 offset:49152
	ds_read_b128 v[192:195], v134 offset:50176
	ds_read_b128 v[196:199], v137 offset:49152
	ds_read_b128 v[220:223], v137 offset:50176
	ds_read_b128 v[224:227], v139 offset:49152
	ds_read_b128 v[232:235], v139 offset:50176
	s_barrier
	s_waitcnt lgkmcnt(0)
	s_setprio 1
	s_waitcnt lgkmcnt(0)
	v_mfma_f32_16x16x32_bf16 v[6:9], v[164:167], v[204:207], v[58:61]
	v_mfma_f32_16x16x32_bf16 v[10:13], v[188:191], v[204:207], v[50:53]
	v_mfma_f32_16x16x32_bf16 v[2:5], v[164:167], v[14:17], v[62:65]
	v_mfma_f32_16x16x32_bf16 v[18:21], v[184:187], v[216:219], v[6:9]
	v_mfma_f32_16x16x32_bf16 v[6:9], v[188:191], v[14:17], v[54:57]
	v_mfma_f32_16x16x32_bf16 v[22:25], v[192:195], v[216:219], v[10:13]
	v_mfma_f32_16x16x32_bf16 v[10:13], v[196:199], v[14:17], v[46:49]
	v_mfma_f32_16x16x32_bf16 v[14:17], v[224:227], v[14:17], v[38:41]
	v_mfma_f32_16x16x32_bf16 v[2:5], v[184:187], v[30:33], v[2:5]
	v_mfma_f32_16x16x32_bf16 v[6:9], v[192:195], v[30:33], v[6:9]
	v_mfma_f32_16x16x32_bf16 v[10:13], v[220:223], v[30:33], v[10:13]
	v_mfma_f32_16x16x32_bf16 v[26:29], v[196:199], v[204:207], v[42:45]
	v_mfma_f32_16x16x32_bf16 v[14:17], v[232:235], v[30:33], v[14:17]
	v_mfma_f32_16x16x32_bf16 v[30:33], v[224:227], v[204:207], v[34:37]
	v_mfma_f32_16x16x32_bf16 v[26:29], v[220:223], v[216:219], v[26:29]
	v_mfma_f32_16x16x32_bf16 v[30:33], v[232:235], v[216:219], v[30:33]
	s_setprio 0
	s_setprio 1
	v_mfma_f32_16x16x32_bf16 v[38:41], v[164:167], v[240:243], v[152:155]
	v_mfma_f32_16x16x32_bf16 v[42:45], v[188:191], v[240:243], v[160:163]
	v_mfma_f32_16x16x32_bf16 v[46:49], v[196:199], v[240:243], v[228:231]
	v_mfma_f32_16x16x32_bf16 v[34:37], v[164:167], v[140:143], v[148:151]
	v_mfma_f32_16x16x32_bf16 v[50:53], v[184:187], v[144:147], v[38:41]
	v_mfma_f32_16x16x32_bf16 v[38:41], v[188:191], v[140:143], v[156:159]
	v_mfma_f32_16x16x32_bf16 v[54:57], v[192:195], v[144:147], v[42:45]
	v_mfma_f32_16x16x32_bf16 v[42:45], v[196:199], v[140:143], v[208:211]
	v_mfma_f32_16x16x32_bf16 v[58:61], v[220:223], v[144:147], v[46:49]
	v_mfma_f32_16x16x32_bf16 v[46:49], v[224:227], v[140:143], v[212:215]
	v_mfma_f32_16x16x32_bf16 v[62:65], v[224:227], v[240:243], v[200:203]
	v_mfma_f32_16x16x32_bf16 v[34:37], v[184:187], v[236:239], v[34:37]
	v_mfma_f32_16x16x32_bf16 v[38:41], v[192:195], v[236:239], v[38:41]
	v_mfma_f32_16x16x32_bf16 v[42:45], v[220:223], v[236:239], v[42:45]
	v_mfma_f32_16x16x32_bf16 v[46:49], v[232:235], v[236:239], v[46:49]
	v_mfma_f32_16x16x32_bf16 v[62:65], v[232:235], v[144:147], v[62:65]
	s_setprio 0
	v_readlane_b32 s4, v245, 33
	v_readlane_b32 s5, v245, 34
	s_and_b64 vcc, exec, s[4:5]
	s_barrier
	s_cbranch_vccz .LBB0_205
	s_barrier

; #define LDA(dst, b, h) for (int m = 0; m < 4; ++m) for (int k = 0; k < 2; ++k) \
;     dst[m][k] = *reinterpret_cast<const bf16x8*>((char*)SA(b, h) + lds_byte(wr * 64 + m * 16 + fr, k * 32 + fq * 8))
; #define LDB(dst, b, h) for (int n = 0; n < 2; ++n) for (int k = 0; k < 2; ++k) \
;     dst[n][k] = *reinterpret_cast<const bf16x8*>((char*)SB(b, h) + lds_byte(wc * 32 + n * 16 + fr, k * 32 + fq * 8))
; #define MMA(ai, bj, At, Bt_) do { __builtin_amdgcn_s_setprio(1); \
;     for (int m = 0; m < 4; ++m) for (int n = 0; n < 2; ++n) for (int k = 0; k < 2; ++k) \
;       acc[ai][bj][m][n] = __builtin_amdgcn_mfma_f32_16x16x32_bf16(At[m][k], Bt_[n][k], acc[ai][bj][m][n], 0, 0, 0); \
;     __builtin_amdgcn_s_setprio(0); } while (0)
; #define WAIT_L(n) asm volatile("s_waitcnt lgkmcnt(" #n ")" ::: "memory")
; #define BAR __builtin_amdgcn_s_barrier()
; #define SCHED __builtin_amdgcn_sched_barrier(0)
;     ...
;       LDB(B0, 0, 0); SCHED; LDA(At, 0, 0); STAGE(SA(1, 1), A, brow + HALF, t + 1);
;       WAIT_L(8); BAR; WAIT_L(0); MMA(0, 0, At, B0); BAR; SCHED;
;       LDB(B1, 0, 1); STAGE(SB(0, 0), Bt, bcol, t + 2);
;       BAR; WAIT_L(0); MMA(0, 1, At, B1); BAR;
;       LDA(At, 0, 1); STAGE(SA(0, 0), A, brow, t + 2);
;       BAR; WAIT_L(0); MMA(1, 0, At, B0); BAR; SCHED;
.LBB0_418:
	v_add_u32_e32 v143, s2, v142
	ds_read_b128 v[146:149], v143
	ds_read_b128 v[150:153], v143 offset:1024
	ds_read_b128 v[154:157], v143 offset:2048
	ds_read_b128 v[158:161], v143 offset:3072
	s_add_u32 s42, s30, s6
	s_addc_u32 s43, s31, s7
	s_add_u32 s44, s42, 0x80080
	s_addc_u32 s45, s43, 0
	s_add_i32 s41, s15, 0xc000
	ds_read_b128 v[162:165], v133
	ds_read_b128 v[184:187], v133 offset:1024
	ds_read_b128 v[188:191], v134
	ds_read_b128 v[192:195], v134 offset:1024
	ds_read_b128 v[196:199], v137
	ds_read_b128 v[200:203], v137 offset:1024
	ds_read_b128 v[204:207], v139
	ds_read_b128 v[208:211], v139 offset:1024
	s_mov_b32 m0, s41
	v_lshl_add_u64 v[144:145], s[44:45], 0, v[0:1]
	s_add_i32 s37, s15, 0xe000
	global_load_lds_dwordx4 v[144:145], off
	v_lshl_add_u64 v[144:145], s[44:45], 0, v[140:141]
	s_mov_b32 m0, s37
	s_nop 0
	global_load_lds_dwordx4 v[144:145], off
	s_waitcnt lgkmcnt(8)
	s_barrier
	s_waitcnt lgkmcnt(0)
	v_mfma_f32_16x16x32_bf16 v[126:129], v[162:165], v[146:149], v[126:129]
	v_mfma_f32_16x16x32_bf16 v[122:125], v[162:165], v[154:157], v[122:125]
	v_mfma_f32_16x16x32_bf16 v[118:121], v[188:191], v[146:149], v[118:121]
	v_mfma_f32_16x16x32_bf16 v[114:117], v[188:191], v[154:157], v[114:117]
	v_mfma_f32_16x16x32_bf16 v[110:113], v[196:199], v[146:149], v[110:113]
	v_mfma_f32_16x16x32_bf16 v[106:109], v[196:199], v[154:157], v[106:109]
	v_mfma_f32_16x16x32_bf16 v[102:105], v[204:207], v[146:149], v[102:105]
	v_mfma_f32_16x16x32_bf16 v[98:101], v[204:207], v[154:157], v[98:101]
	v_mfma_f32_16x16x32_bf16 v[126:129], v[184:187], v[150:153], v[126:129]
	v_mfma_f32_16x16x32_bf16 v[122:125], v[184:187], v[158:161], v[122:125]
	v_mfma_f32_16x16x32_bf16 v[118:121], v[192:195], v[150:153], v[118:121]
	v_mfma_f32_16x16x32_bf16 v[114:117], v[192:195], v[158:161], v[114:117]
	v_mfma_f32_16x16x32_bf16 v[110:113], v[200:203], v[150:153], v[110:113]
	v_mfma_f32_16x16x32_bf16 v[106:109], v[200:203], v[158:161], v[106:109]
	v_mfma_f32_16x16x32_bf16 v[102:105], v[208:211], v[150:153], v[102:105]
	v_mfma_f32_16x16x32_bf16 v[98:101], v[208:211], v[158:161], v[98:101]
	s_barrier
	s_add_u32 s44, s34, s6
	s_addc_u32 s45, s35, s7
	s_add_u32 s50, s44, 0x100
	v_add_u32_e32 v144, s76, v142
	s_addc_u32 s51, s45, 0
	s_mov_b32 m0, s23
	ds_read_b128 v[212:215], v144
	ds_read_b128 v[216:219], v144 offset:1024
	ds_read_b128 v[220:223], v144 offset:2048
	ds_read_b128 v[224:227], v144 offset:3072
	s_nop 0
	v_lshl_add_u64 v[166:167], s[50:51], 0, v[0:1]
	global_load_lds_dwordx4 v[166:167], off
	v_lshl_add_u64 v[166:167], s[50:51], 0, v[140:141]
	s_mov_b32 m0, s26
	s_nop 0
	global_load_lds_dwordx4 v[166:167], off
	s_barrier
	s_waitcnt lgkmcnt(0)
	v_mfma_f32_16x16x32_bf16 v[94:97], v[162:165], v[212:215], v[94:97]
	v_mfma_f32_16x16x32_bf16 v[90:93], v[162:165], v[220:223], v[90:93]
	v_mfma_f32_16x16x32_bf16 v[86:89], v[188:191], v[212:215], v[86:89]
	v_mfma_f32_16x16x32_bf16 v[82:85], v[188:191], v[220:223], v[82:85]
	v_mfma_f32_16x16x32_bf16 v[78:81], v[196:199], v[212:215], v[78:81]
	v_mfma_f32_16x16x32_bf16 v[74:77], v[196:199], v[220:223], v[74:77]
	v_mfma_f32_16x16x32_bf16 v[70:73], v[204:207], v[212:215], v[70:73]
	v_mfma_f32_16x16x32_bf16 v[66:69], v[204:207], v[220:223], v[66:69]
	v_mfma_f32_16x16x32_bf16 v[94:97], v[184:187], v[216:219], v[94:97]
	v_mfma_f32_16x16x32_bf16 v[90:93], v[184:187], v[224:227], v[90:93]
	v_mfma_f32_16x16x32_bf16 v[86:89], v[192:195], v[216:219], v[86:89]
	v_mfma_f32_16x16x32_bf16 v[82:85], v[192:195], v[224:227], v[82:85]
	v_mfma_f32_16x16x32_bf16 v[78:81], v[200:203], v[216:219], v[78:81]
	v_mfma_f32_16x16x32_bf16 v[74:77], v[200:203], v[224:227], v[74:77]
	v_mfma_f32_16x16x32_bf16 v[70:73], v[208:211], v[216:219], v[70:73]
	v_mfma_f32_16x16x32_bf16 v[66:69], v[208:211], v[224:227], v[66:69]
	s_add_u32 s50, s42, 0x100
	s_addc_u32 s51, s43, 0
	s_mov_b32 m0, s15
	s_barrier
	ds_read_b128 v[162:165], v133 offset:16384
	ds_read_b128 v[184:187], v133 offset:17408
	ds_read_b128 v[188:191], v134 offset:16384
	ds_read_b128 v[192:195], v134 offset:17408
	ds_read_b128 v[196:199], v137 offset:16384
	ds_read_b128 v[200:203], v137 offset:17408
	ds_read_b128 v[204:207], v139 offset:16384
	ds_read_b128 v[208:211], v139 offset:17408
	s_nop 0
	v_lshl_add_u64 v[166:167], s[50:51], 0, v[0:1]
	global_load_lds_dwordx4 v[166:167], off
	v_lshl_add_u64 v[166:167], s[50:51], 0, v[140:141]
	s_mov_b32 m0, s25
	s_nop 0
	global_load_lds_dwordx4 v[166:167], off
	s_barrier
	s_waitcnt lgkmcnt(0)
	v_mfma_f32_16x16x32_bf16 v[62:65], v[162:165], v[146:149], v[62:65]
	v_mfma_f32_16x16x32_bf16 v[58:61], v[162:165], v[154:157], v[58:61]
	v_mfma_f32_16x16x32_bf16 v[54:57], v[188:191], v[146:149], v[54:57]
	v_mfma_f32_16x16x32_bf16 v[50:53], v[188:191], v[154:157], v[50:53]
	v_mfma_f32_16x16x32_bf16 v[46:49], v[196:199], v[146:149], v[46:49]
	v_mfma_f32_16x16x32_bf16 v[42:45], v[196:199], v[154:157], v[42:45]
	v_mfma_f32_16x16x32_bf16 v[38:41], v[204:207], v[146:149], v[38:41]
	v_mfma_f32_16x16x32_bf16 v[34:37], v[204:207], v[154:157], v[34:37]
	v_mfma_f32_16x16x32_bf16 v[62:65], v[184:187], v[150:153], v[62:65]
	v_mfma_f32_16x16x32_bf16 v[58:61], v[184:187], v[158:161], v[58:61]
	v_mfma_f32_16x16x32_bf16 v[54:57], v[192:195], v[150:153], v[54:57]
	v_mfma_f32_16x16x32_bf16 v[50:53], v[192:195], v[158:161], v[50:53]
	v_mfma_f32_16x16x32_bf16 v[46:49], v[200:203], v[150:153], v[46:49]
	v_mfma_f32_16x16x32_bf16 v[42:45], v[200:203], v[158:161], v[42:45]
	v_mfma_f32_16x16x32_bf16 v[38:41], v[208:211], v[150:153], v[38:41]
	v_mfma_f32_16x16x32_bf16 v[34:37], v[208:211], v[158:161], v[34:37]
	s_barrier
; #define LDA(dst, b, h) for (int m = 0; m < 4; ++m) for (int k = 0; k < 2; ++k) \
;     dst[m][k] = *reinterpret_cast<const bf16x8*>((char*)SA(b, h) + lds_byte(wr * 64 + m * 16 + fr, k * 32 + fq * 8))
; #define LDB(dst, b, h) for (int n = 0; n < 2; ++n) for (int k = 0; k < 2; ++k) \
;     dst[n][k] = *reinterpret_cast<const bf16x8*>((char*)SB(b, h) + lds_byte(wc * 32 + n * 16 + fr, k * 32 + fq * 8))
; #define MMA(ai, bj, At, Bt_) do { __builtin_amdgcn_s_setprio(1); \
;     for (int m = 0; m < 4; ++m) for (int n = 0; n < 2; ++n) for (int k = 0; k < 2; ++k) \
;       acc[ai][bj][m][n] = __builtin_amdgcn_mfma_f32_16x16x32_bf16(At[m][k], Bt_[n][k], acc[ai][bj][m][n], 0, 0, 0); \
;     __builtin_amdgcn_s_setprio(0); } while (0)
; #define WAIT_V(n) asm volatile("s_waitcnt vmcnt(" #n ")" ::: "memory")
; #define WAIT_L(n) asm volatile("s_waitcnt lgkmcnt(" #n ")" ::: "memory")
; #define BAR __builtin_amdgcn_s_barrier()
; #define SCHED __builtin_amdgcn_sched_barrier(0)
;     ...
;       STAGE(SB(0, 1), Bt, bcol + HALF, t + 2);
;       WAIT_V(6); BAR; MMA(1, 1, At, B1); BAR;
;       LDB(B0, 1, 0); SCHED; LDA(At, 1, 0); STAGE(SA(0, 1), A, brow + HALF, t + 2);
;       WAIT_L(8); BAR; WAIT_L(0); MMA(0, 0, At, B0); BAR; SCHED;
;       LDB(B1, 1, 1); STAGE(SB(1, 0), Bt, bcol, t + 3);
;       BAR; WAIT_L(0); MMA(0, 1, At, B1); BAR;
;       LDA(At, 1, 1); STAGE(SA(1, 0), A, brow, t + 3);
	s_add_u32 s50, s44, 0x80100
	s_addc_u32 s51, s45, 0
	s_mov_b32 m0, s27
	s_nop 0
	v_lshl_add_u64 v[146:147], s[50:51], 0, v[0:1]
	global_load_lds_dwordx4 v[146:147], off
	v_lshl_add_u64 v[146:147], s[50:51], 0, v[140:141]
	s_mov_b32 m0, s28
	s_nop 0
	global_load_lds_dwordx4 v[146:147], off
	s_waitcnt vmcnt(6)
	s_barrier
	v_mfma_f32_16x16x32_bf16 v[30:33], v[162:165], v[212:215], v[30:33]
	v_mfma_f32_16x16x32_bf16 v[26:29], v[162:165], v[220:223], v[26:29]
	v_mfma_f32_16x16x32_bf16 v[22:25], v[188:191], v[212:215], v[22:25]
	v_mfma_f32_16x16x32_bf16 v[18:21], v[188:191], v[220:223], v[18:21]
	v_mfma_f32_16x16x32_bf16 v[14:17], v[196:199], v[212:215], v[14:17]
	v_mfma_f32_16x16x32_bf16 v[10:13], v[196:199], v[220:223], v[10:13]
	v_mfma_f32_16x16x32_bf16 v[6:9], v[204:207], v[212:215], v[6:9]
	v_mfma_f32_16x16x32_bf16 v[2:5], v[204:207], v[220:223], v[2:5]
	v_mfma_f32_16x16x32_bf16 v[30:33], v[184:187], v[216:219], v[30:33]
	v_mfma_f32_16x16x32_bf16 v[26:29], v[184:187], v[224:227], v[26:29]
	v_mfma_f32_16x16x32_bf16 v[22:25], v[192:195], v[216:219], v[22:25]
	v_mfma_f32_16x16x32_bf16 v[18:21], v[192:195], v[224:227], v[18:21]
	v_mfma_f32_16x16x32_bf16 v[14:17], v[200:203], v[216:219], v[14:17]
	v_mfma_f32_16x16x32_bf16 v[10:13], v[200:203], v[224:227], v[10:13]
	v_mfma_f32_16x16x32_bf16 v[6:9], v[208:211], v[216:219], v[6:9]
	v_mfma_f32_16x16x32_bf16 v[2:5], v[208:211], v[224:227], v[2:5]
	v_add_u32_e32 v145, s77, v142
	s_barrier
	ds_read_b128 v[148:151], v145
	ds_read_b128 v[152:155], v145 offset:1024
	ds_read_b128 v[156:159], v145 offset:2048
	ds_read_b128 v[160:163], v145 offset:3072
	s_add_u32 s50, s42, 0x80100
	s_addc_u32 s51, s43, 0
	s_mov_b32 m0, s17
	ds_read_b128 v[164:167], v133 offset:32768
	ds_read_b128 v[184:187], v133 offset:33792
	ds_read_b128 v[188:191], v134 offset:32768
	ds_read_b128 v[192:195], v134 offset:33792
	ds_read_b128 v[196:199], v137 offset:32768
	ds_read_b128 v[200:203], v137 offset:33792
	ds_read_b128 v[204:207], v139 offset:32768
	ds_read_b128 v[208:211], v139 offset:33792
	s_nop 0
	v_lshl_add_u64 v[146:147], s[50:51], 0, v[0:1]
	global_load_lds_dwordx4 v[146:147], off
	v_lshl_add_u64 v[146:147], s[50:51], 0, v[140:141]
	s_mov_b32 m0, s29
	s_nop 0
	global_load_lds_dwordx4 v[146:147], off
	s_waitcnt lgkmcnt(8)
	s_barrier
	s_waitcnt lgkmcnt(0)
	v_mfma_f32_16x16x32_bf16 v[126:129], v[164:167], v[148:151], v[126:129]
	v_mfma_f32_16x16x32_bf16 v[122:125], v[164:167], v[156:159], v[122:125]
	v_mfma_f32_16x16x32_bf16 v[118:121], v[188:191], v[148:151], v[118:121]
	v_mfma_f32_16x16x32_bf16 v[114:117], v[188:191], v[156:159], v[114:117]
	v_mfma_f32_16x16x32_bf16 v[110:113], v[196:199], v[148:151], v[110:113]
	v_mfma_f32_16x16x32_bf16 v[106:109], v[196:199], v[156:159], v[106:109]
	v_mfma_f32_16x16x32_bf16 v[102:105], v[204:207], v[148:151], v[102:105]
	v_mfma_f32_16x16x32_bf16 v[98:101], v[204:207], v[156:159], v[98:101]
	v_mfma_f32_16x16x32_bf16 v[126:129], v[184:187], v[152:155], v[126:129]
	v_mfma_f32_16x16x32_bf16 v[122:125], v[184:187], v[160:163], v[122:125]
	v_mfma_f32_16x16x32_bf16 v[118:121], v[192:195], v[152:155], v[118:121]
	v_mfma_f32_16x16x32_bf16 v[114:117], v[192:195], v[160:163], v[114:117]
	v_mfma_f32_16x16x32_bf16 v[110:113], v[200:203], v[152:155], v[110:113]
	v_mfma_f32_16x16x32_bf16 v[106:109], v[200:203], v[160:163], v[106:109]
	v_mfma_f32_16x16x32_bf16 v[102:105], v[208:211], v[152:155], v[102:105]
	v_mfma_f32_16x16x32_bf16 v[98:101], v[208:211], v[160:163], v[98:101]
	s_barrier
	s_add_u32 s50, s44, 0x180
	v_add_u32_e32 v146, s78, v142
	s_addc_u32 s51, s45, 0
	s_mov_b32 m0, s8
	ds_read_b128 v[212:215], v146
	ds_read_b128 v[216:219], v146 offset:1024
	ds_read_b128 v[220:223], v146 offset:2048
	ds_read_b128 v[224:227], v146 offset:3072
	s_nop 0
	v_lshl_add_u64 v[228:229], s[50:51], 0, v[0:1]
	global_load_lds_dwordx4 v[228:229], off
	v_lshl_add_u64 v[228:229], s[50:51], 0, v[140:141]
	s_mov_b32 m0, s9
	s_nop 0
	global_load_lds_dwordx4 v[228:229], off
	s_barrier
	s_waitcnt lgkmcnt(0)
	v_mfma_f32_16x16x32_bf16 v[94:97], v[164:167], v[212:215], v[94:97]
	v_mfma_f32_16x16x32_bf16 v[90:93], v[164:167], v[220:223], v[90:93]
	v_mfma_f32_16x16x32_bf16 v[86:89], v[188:191], v[212:215], v[86:89]
	v_mfma_f32_16x16x32_bf16 v[82:85], v[188:191], v[220:223], v[82:85]
	v_mfma_f32_16x16x32_bf16 v[78:81], v[196:199], v[212:215], v[78:81]
	v_mfma_f32_16x16x32_bf16 v[74:77], v[196:199], v[220:223], v[74:77]
	v_mfma_f32_16x16x32_bf16 v[70:73], v[204:207], v[212:215], v[70:73]
	v_mfma_f32_16x16x32_bf16 v[66:69], v[204:207], v[220:223], v[66:69]
	v_mfma_f32_16x16x32_bf16 v[94:97], v[184:187], v[216:219], v[94:97]
	v_mfma_f32_16x16x32_bf16 v[90:93], v[184:187], v[224:227], v[90:93]
	v_mfma_f32_16x16x32_bf16 v[86:89], v[192:195], v[216:219], v[86:89]
	v_mfma_f32_16x16x32_bf16 v[82:85], v[192:195], v[224:227], v[82:85]
	v_mfma_f32_16x16x32_bf16 v[78:81], v[200:203], v[216:219], v[78:81]
	v_mfma_f32_16x16x32_bf16 v[74:77], v[200:203], v[224:227], v[74:77]
	v_mfma_f32_16x16x32_bf16 v[70:73], v[208:211], v[216:219], v[70:73]
	v_mfma_f32_16x16x32_bf16 v[66:69], v[208:211], v[224:227], v[66:69]
	s_add_u32 s42, s42, 0x180
	s_addc_u32 s43, s43, 0
	s_mov_b32 m0, s18
	s_barrier
	ds_read_b128 v[164:167], v133 offset:49152
	ds_read_b128 v[184:187], v133 offset:50176
	ds_read_b128 v[188:191], v134 offset:49152
	ds_read_b128 v[192:195], v134 offset:50176
	ds_read_b128 v[196:199], v137 offset:49152
	ds_read_b128 v[200:203], v137 offset:50176
	ds_read_b128 v[204:207], v139 offset:49152
	ds_read_b128 v[208:211], v139 offset:50176
	s_nop 0
	v_lshl_add_u64 v[228:229], s[42:43], 0, v[0:1]
	global_load_lds_dwordx4 v[228:229], off
	v_lshl_add_u64 v[228:229], s[42:43], 0, v[140:141]
	s_mov_b32 m0, s19
	s_nop 0
	global_load_lds_dwordx4 v[228:229], off
	s_barrier
; #define LDA(dst, b, h) for (int m = 0; m < 4; ++m) for (int k = 0; k < 2; ++k) \
;     dst[m][k] = *reinterpret_cast<const bf16x8*>((char*)SA(b, h) + lds_byte(wr * 64 + m * 16 + fr, k * 32 + fq * 8))
; #define LDB(dst, b, h) for (int n = 0; n < 2; ++n) for (int k = 0; k < 2; ++k) \
;     dst[n][k] = *reinterpret_cast<const bf16x8*>((char*)SB(b, h) + lds_byte(wc * 32 + n * 16 + fr, k * 32 + fq * 8))
; #define MMA(ai, bj, At, Bt_) do { __builtin_amdgcn_s_setprio(1); \
;     for (int m = 0; m < 4; ++m) for (int n = 0; n < 2; ++n) for (int k = 0; k < 2; ++k) \
;       acc[ai][bj][m][n] = __builtin_amdgcn_mfma_f32_16x16x32_bf16(At[m][k], Bt_[n][k], acc[ai][bj][m][n], 0, 0, 0); \
;     __builtin_amdgcn_s_setprio(0); } while (0)
; #define WAIT_V(n) asm volatile("s_waitcnt vmcnt(" #n ")" ::: "memory")
; #define WAIT_L(n) asm volatile("s_waitcnt lgkmcnt(" #n ")" ::: "memory")
; #define BAR __builtin_amdgcn_s_barrier()
; #define SCHED __builtin_amdgcn_sched_barrier(0)
;     ...
;       BAR; WAIT_L(0); MMA(1, 0, At, B0); BAR; SCHED;
;       STAGE(SB(1, 1), Bt, bcol + HALF, t + 3);
;       WAIT_V(6); BAR; MMA(1, 1, At, B1); BAR;
;     }
;     { LDB(B0, 0, 0); LDA(At, 0, 0); STAGE(SA(1, 1), A, brow + HALF, nt - 1);
;       BAR; WAIT_L(0); MMA(0, 0, At, B0); BAR;
;       LDB(B1, 0, 1); BAR; WAIT_L(0); MMA(0, 1, At, B1); BAR;
	s_waitcnt lgkmcnt(0)
	v_mfma_f32_16x16x32_bf16 v[62:65], v[164:167], v[148:151], v[62:65]
	v_mfma_f32_16x16x32_bf16 v[58:61], v[164:167], v[156:159], v[58:61]
	v_mfma_f32_16x16x32_bf16 v[54:57], v[188:191], v[148:151], v[54:57]
	v_mfma_f32_16x16x32_bf16 v[50:53], v[188:191], v[156:159], v[50:53]
	v_mfma_f32_16x16x32_bf16 v[46:49], v[196:199], v[148:151], v[46:49]
	v_mfma_f32_16x16x32_bf16 v[42:45], v[196:199], v[156:159], v[42:45]
	v_mfma_f32_16x16x32_bf16 v[38:41], v[204:207], v[148:151], v[38:41]
	v_mfma_f32_16x16x32_bf16 v[34:37], v[204:207], v[156:159], v[34:37]
	v_mfma_f32_16x16x32_bf16 v[62:65], v[184:187], v[152:155], v[62:65]
	v_mfma_f32_16x16x32_bf16 v[58:61], v[184:187], v[160:163], v[58:61]
	v_mfma_f32_16x16x32_bf16 v[54:57], v[192:195], v[152:155], v[54:57]
	v_mfma_f32_16x16x32_bf16 v[50:53], v[192:195], v[160:163], v[50:53]
	v_mfma_f32_16x16x32_bf16 v[46:49], v[200:203], v[152:155], v[46:49]
	v_mfma_f32_16x16x32_bf16 v[42:45], v[200:203], v[160:163], v[42:45]
	v_mfma_f32_16x16x32_bf16 v[38:41], v[208:211], v[152:155], v[38:41]
	v_mfma_f32_16x16x32_bf16 v[34:37], v[208:211], v[160:163], v[34:37]
	s_barrier
	s_add_u32 s42, s44, 0x80180
	s_addc_u32 s43, s45, 0
	s_mov_b32 m0, s20
	s_nop 0
	v_lshl_add_u64 v[148:149], s[42:43], 0, v[0:1]
	global_load_lds_dwordx4 v[148:149], off
	v_lshl_add_u64 v[148:149], s[42:43], 0, v[140:141]
	s_mov_b32 m0, s21
	s_nop 0
	global_load_lds_dwordx4 v[148:149], off
	s_waitcnt vmcnt(6)
	s_barrier
	v_mfma_f32_16x16x32_bf16 v[30:33], v[164:167], v[212:215], v[30:33]
	v_mfma_f32_16x16x32_bf16 v[26:29], v[164:167], v[220:223], v[26:29]
	v_mfma_f32_16x16x32_bf16 v[22:25], v[188:191], v[212:215], v[22:25]
	v_mfma_f32_16x16x32_bf16 v[18:21], v[188:191], v[220:223], v[18:21]
	v_mfma_f32_16x16x32_bf16 v[14:17], v[196:199], v[212:215], v[14:17]
	v_mfma_f32_16x16x32_bf16 v[10:13], v[196:199], v[220:223], v[10:13]
	v_mfma_f32_16x16x32_bf16 v[6:9], v[204:207], v[212:215], v[6:9]
	v_mfma_f32_16x16x32_bf16 v[2:5], v[204:207], v[220:223], v[2:5]
	v_mfma_f32_16x16x32_bf16 v[30:33], v[184:187], v[216:219], v[30:33]
	v_mfma_f32_16x16x32_bf16 v[26:29], v[184:187], v[224:227], v[26:29]
	v_mfma_f32_16x16x32_bf16 v[22:25], v[192:195], v[216:219], v[22:25]
	v_mfma_f32_16x16x32_bf16 v[18:21], v[192:195], v[224:227], v[18:21]
	v_mfma_f32_16x16x32_bf16 v[14:17], v[200:203], v[216:219], v[14:17]
	v_mfma_f32_16x16x32_bf16 v[10:13], v[200:203], v[224:227], v[10:13]
	v_mfma_f32_16x16x32_bf16 v[6:9], v[208:211], v[216:219], v[6:9]
	v_mfma_f32_16x16x32_bf16 v[2:5], v[208:211], v[224:227], v[2:5]
	s_add_i32 s36, s36, 2
	s_add_u32 s6, s6, 0x100
	s_addc_u32 s7, s7, 0
	s_cmp_gt_u32 s36, 27
	s_barrier
	s_cbranch_scc0 .LBB0_418
	s_add_u32 s4, s4, 0xf80
	s_addc_u32 s5, s5, 0
	s_mov_b32 m0, s41
	ds_read_b128 v[148:151], v143
	ds_read_b128 v[152:155], v143 offset:1024
	ds_read_b128 v[156:159], v143 offset:2048
	ds_read_b128 v[160:163], v143 offset:3072
	ds_read_b128 v[164:167], v133
	ds_read_b128 v[184:187], v133 offset:1024
	ds_read_b128 v[188:191], v134
	ds_read_b128 v[192:195], v134 offset:1024
	ds_read_b128 v[196:199], v137
	ds_read_b128 v[200:203], v137 offset:1024
	ds_read_b128 v[204:207], v139
	ds_read_b128 v[208:211], v139 offset:1024
	s_nop 0
	v_lshl_add_u64 v[142:143], s[4:5], 0, v[0:1]
	global_load_lds_dwordx4 v[142:143], off
	v_lshl_add_u64 v[140:141], s[4:5], 0, v[140:141]
	s_mov_b32 m0, s37
	s_nop 0
	global_load_lds_dwordx4 v[140:141], off
	s_barrier
	s_waitcnt lgkmcnt(0)
	s_setprio 1
	s_waitcnt lgkmcnt(0)
	v_mfma_f32_16x16x32_bf16 v[126:129], v[164:167], v[148:151], v[126:129]
	v_mfma_f32_16x16x32_bf16 v[122:125], v[164:167], v[156:159], v[122:125]
	v_mfma_f32_16x16x32_bf16 v[118:121], v[188:191], v[148:151], v[118:121]
	v_mfma_f32_16x16x32_bf16 v[110:113], v[196:199], v[148:151], v[110:113]
	v_mfma_f32_16x16x32_bf16 v[106:109], v[196:199], v[156:159], v[106:109]
	v_mfma_f32_16x16x32_bf16 v[102:105], v[204:207], v[148:151], v[102:105]
	v_mfma_f32_16x16x32_bf16 v[98:101], v[204:207], v[156:159], v[98:101]
	v_mfma_f32_16x16x32_bf16 v[126:129], v[184:187], v[152:155], v[126:129]
	v_mfma_f32_16x16x32_bf16 v[122:125], v[184:187], v[160:163], v[122:125]
	v_mfma_f32_16x16x32_bf16 v[118:121], v[192:195], v[152:155], v[118:121]
	v_mfma_f32_16x16x32_bf16 v[114:117], v[188:191], v[156:159], v[114:117]
	v_mfma_f32_16x16x32_bf16 v[110:113], v[200:203], v[152:155], v[110:113]
	v_mfma_f32_16x16x32_bf16 v[106:109], v[200:203], v[160:163], v[106:109]
	v_mfma_f32_16x16x32_bf16 v[102:105], v[208:211], v[152:155], v[102:105]
	v_mfma_f32_16x16x32_bf16 v[98:101], v[208:211], v[160:163], v[98:101]
	v_mfma_f32_16x16x32_bf16 v[140:143], v[192:195], v[160:163], v[114:117]
	s_setprio 0
	s_barrier
	s_nop 0
	ds_read_b128 v[114:117], v144
	ds_read_b128 v[212:215], v144 offset:1024
	ds_read_b128 v[216:219], v144 offset:2048
	ds_read_b128 v[220:223], v144 offset:3072
	s_barrier
	s_waitcnt lgkmcnt(0)
	s_setprio 1
	s_waitcnt lgkmcnt(0)
	v_mfma_f32_16x16x32_bf16 v[90:93], v[164:167], v[216:219], v[90:93]
	v_mfma_f32_16x16x32_bf16 v[86:89], v[188:191], v[114:117], v[86:89]
	v_mfma_f32_16x16x32_bf16 v[94:97], v[164:167], v[114:117], v[94:97]
	v_mfma_f32_16x16x32_bf16 v[90:93], v[184:187], v[220:223], v[90:93]
	v_mfma_f32_16x16x32_bf16 v[86:89], v[192:195], v[212:215], v[86:89]
	v_mfma_f32_16x16x32_bf16 v[82:85], v[188:191], v[216:219], v[82:85]
	v_mfma_f32_16x16x32_bf16 v[78:81], v[196:199], v[114:117], v[78:81]
	v_mfma_f32_16x16x32_bf16 v[74:77], v[196:199], v[216:219], v[74:77]
	v_mfma_f32_16x16x32_bf16 v[70:73], v[204:207], v[114:117], v[70:73]
	v_mfma_f32_16x16x32_bf16 v[66:69], v[204:207], v[216:219], v[66:69]
	v_mfma_f32_16x16x32_bf16 v[224:227], v[184:187], v[212:215], v[94:97]
	v_mfma_f32_16x16x32_bf16 v[164:167], v[192:195], v[220:223], v[82:85]
	v_mfma_f32_16x16x32_bf16 v[184:187], v[200:203], v[212:215], v[78:81]
	v_mfma_f32_16x16x32_bf16 v[188:191], v[200:203], v[220:223], v[74:77]
	v_mfma_f32_16x16x32_bf16 v[192:195], v[208:211], v[212:215], v[70:73]
	v_mfma_f32_16x16x32_bf16 v[196:199], v[208:211], v[220:223], v[66:69]
	s_setprio 0
	s_barrier
; #define LDA(dst, b, h) for (int m = 0; m < 4; ++m) for (int k = 0; k < 2; ++k) \
;     dst[m][k] = *reinterpret_cast<const bf16x8*>((char*)SA(b, h) + lds_byte(wr * 64 + m * 16 + fr, k * 32 + fq * 8))
; #define LDB(dst, b, h) for (int n = 0; n < 2; ++n) for (int k = 0; k < 2; ++k) \
;     dst[n][k] = *reinterpret_cast<const bf16x8*>((char*)SB(b, h) + lds_byte(wc * 32 + n * 16 + fr, k * 32 + fq * 8))
; #define MMA(ai, bj, At, Bt_) do { __builtin_amdgcn_s_setprio(1); \
;     for (int m = 0; m < 4; ++m) for (int n = 0; n < 2; ++n) for (int k = 0; k < 2; ++k) \
;       acc[ai][bj][m][n] = __builtin_amdgcn_mfma_f32_16x16x32_bf16(At[m][k], Bt_[n][k], acc[ai][bj][m][n], 0, 0, 0); \
;     __builtin_amdgcn_s_setprio(0); } while (0)
; #define WAIT_V(n) asm volatile("s_waitcnt vmcnt(" #n ")" ::: "memory")
; #define WAIT_L(n) asm volatile("s_waitcnt lgkmcnt(" #n ")" ::: "memory")
; #define BAR __builtin_amdgcn_s_barrier()
;     ...
;       LDB(B1, 0, 1); BAR; WAIT_L(0); MMA(0, 1, At, B1); BAR;
;       LDA(At, 0, 1); WAIT_V(4); BAR; WAIT_L(0); MMA(1, 0, At, B0); MMA(1, 1, At, B1); BAR; }
;     { LDB(B0, 1, 0); LDA(At, 1, 0); WAIT_V(2); BAR; WAIT_L(0); MMA(0, 0, At, B0); BAR;
;       LDB(B1, 1, 1); WAIT_V(0); BAR; WAIT_L(0); MMA(0, 1, At, B1); BAR;
	s_nop 0
	ds_read_b128 v[66:69], v133 offset:16384
	ds_read_b128 v[70:73], v133 offset:17408
	ds_read_b128 v[74:77], v134 offset:16384
	ds_read_b128 v[78:81], v134 offset:17408
	ds_read_b128 v[82:85], v137 offset:16384
	ds_read_b128 v[94:97], v137 offset:17408
	ds_read_b128 v[200:203], v139 offset:16384
	ds_read_b128 v[204:207], v139 offset:17408
	s_waitcnt vmcnt(4)
	s_barrier
	s_waitcnt lgkmcnt(0)
	s_setprio 1
	s_waitcnt lgkmcnt(0)
	v_mfma_f32_16x16x32_bf16 v[62:65], v[66:69], v[148:151], v[62:65]
	v_mfma_f32_16x16x32_bf16 v[58:61], v[66:69], v[156:159], v[58:61]
	v_mfma_f32_16x16x32_bf16 v[54:57], v[74:77], v[148:151], v[54:57]
	v_mfma_f32_16x16x32_bf16 v[50:53], v[74:77], v[156:159], v[50:53]
	v_mfma_f32_16x16x32_bf16 v[46:49], v[82:85], v[148:151], v[46:49]
	v_mfma_f32_16x16x32_bf16 v[42:45], v[82:85], v[156:159], v[42:45]
	v_mfma_f32_16x16x32_bf16 v[38:41], v[200:203], v[148:151], v[38:41]
	v_mfma_f32_16x16x32_bf16 v[34:37], v[200:203], v[156:159], v[34:37]
	v_mfma_f32_16x16x32_bf16 v[62:65], v[70:73], v[152:155], v[62:65]
	v_mfma_f32_16x16x32_bf16 v[58:61], v[70:73], v[160:163], v[58:61]
	v_mfma_f32_16x16x32_bf16 v[54:57], v[78:81], v[152:155], v[54:57]
	v_mfma_f32_16x16x32_bf16 v[50:53], v[78:81], v[160:163], v[50:53]
	v_mfma_f32_16x16x32_bf16 v[46:49], v[94:97], v[152:155], v[46:49]
	v_mfma_f32_16x16x32_bf16 v[42:45], v[94:97], v[160:163], v[42:45]
	v_mfma_f32_16x16x32_bf16 v[38:41], v[204:207], v[152:155], v[38:41]
	v_mfma_f32_16x16x32_bf16 v[34:37], v[204:207], v[160:163], v[34:37]
	s_setprio 0
	s_setprio 1
	v_mfma_f32_16x16x32_bf16 v[30:33], v[66:69], v[114:117], v[30:33]
	v_mfma_f32_16x16x32_bf16 v[26:29], v[66:69], v[216:219], v[26:29]
	v_mfma_f32_16x16x32_bf16 v[22:25], v[74:77], v[114:117], v[22:25]
	v_mfma_f32_16x16x32_bf16 v[18:21], v[74:77], v[216:219], v[18:21]
	v_mfma_f32_16x16x32_bf16 v[14:17], v[82:85], v[114:117], v[14:17]
	v_mfma_f32_16x16x32_bf16 v[10:13], v[82:85], v[216:219], v[10:13]
	v_mfma_f32_16x16x32_bf16 v[6:9], v[200:203], v[114:117], v[6:9]
	v_mfma_f32_16x16x32_bf16 v[2:5], v[200:203], v[216:219], v[2:5]
	v_mfma_f32_16x16x32_bf16 v[148:151], v[70:73], v[212:215], v[30:33]
	v_mfma_f32_16x16x32_bf16 v[152:155], v[70:73], v[220:223], v[26:29]
	v_mfma_f32_16x16x32_bf16 v[156:159], v[78:81], v[212:215], v[22:25]
	v_mfma_f32_16x16x32_bf16 v[160:163], v[78:81], v[220:223], v[18:21]
	v_mfma_f32_16x16x32_bf16 v[208:211], v[94:97], v[212:215], v[14:17]
	v_mfma_f32_16x16x32_bf16 v[228:231], v[94:97], v[220:223], v[10:13]
	v_mfma_f32_16x16x32_bf16 v[212:215], v[204:207], v[212:215], v[6:9]
	v_mfma_f32_16x16x32_bf16 v[200:203], v[204:207], v[220:223], v[2:5]
	s_setprio 0
	s_barrier
	ds_read_b128 v[14:17], v145
	ds_read_b128 v[30:33], v145 offset:1024
	ds_read_b128 v[204:207], v145 offset:2048
	ds_read_b128 v[216:219], v145 offset:3072
	ds_read_b128 v[2:5], v133 offset:32768
	ds_read_b128 v[6:9], v133 offset:33792
	ds_read_b128 v[10:13], v134 offset:32768
	ds_read_b128 v[18:21], v134 offset:33792
	ds_read_b128 v[22:25], v137 offset:32768
	ds_read_b128 v[26:29], v137 offset:33792
	ds_read_b128 v[220:223], v139 offset:32768
	ds_read_b128 v[232:235], v139 offset:33792
	s_waitcnt vmcnt(2)
	s_barrier
	s_waitcnt lgkmcnt(0)
	s_setprio 1
	s_waitcnt lgkmcnt(0)
	v_mfma_f32_16x16x32_bf16 v[66:69], v[2:5], v[14:17], v[126:129]
	v_mfma_f32_16x16x32_bf16 v[114:117], v[6:9], v[30:33], v[66:69]
	v_mfma_f32_16x16x32_bf16 v[66:69], v[2:5], v[204:207], v[122:125]
	v_mfma_f32_16x16x32_bf16 v[126:129], v[6:9], v[216:219], v[66:69]
	v_mfma_f32_16x16x32_bf16 v[66:69], v[10:13], v[14:17], v[118:121]
	v_mfma_f32_16x16x32_bf16 v[82:85], v[18:21], v[30:33], v[66:69]
	v_mfma_f32_16x16x32_bf16 v[66:69], v[10:13], v[204:207], v[140:143]
	v_mfma_f32_16x16x32_bf16 v[94:97], v[18:21], v[216:219], v[66:69]
	v_mfma_f32_16x16x32_bf16 v[66:69], v[22:25], v[14:17], v[110:113]
	v_mfma_f32_16x16x32_bf16 v[74:77], v[26:29], v[30:33], v[66:69]
	v_mfma_f32_16x16x32_bf16 v[66:69], v[22:25], v[204:207], v[106:109]
	v_mfma_f32_16x16x32_bf16 v[78:81], v[26:29], v[216:219], v[66:69]
	v_mfma_f32_16x16x32_bf16 v[66:69], v[220:223], v[14:17], v[102:105]
	v_mfma_f32_16x16x32_bf16 v[70:73], v[220:223], v[204:207], v[98:101]
	v_mfma_f32_16x16x32_bf16 v[66:69], v[232:235], v[30:33], v[66:69]
	v_mfma_f32_16x16x32_bf16 v[70:73], v[232:235], v[216:219], v[70:73]
	s_setprio 0
	s_barrier
; #define LDA(dst, b, h) for (int m = 0; m < 4; ++m) for (int k = 0; k < 2; ++k) \
;     dst[m][k] = *reinterpret_cast<const bf16x8*>((char*)SA(b, h) + lds_byte(wr * 64 + m * 16 + fr, k * 32 + fq * 8))
; #define LDB(dst, b, h) for (int n = 0; n < 2; ++n) for (int k = 0; k < 2; ++k) \
;     dst[n][k] = *reinterpret_cast<const bf16x8*>((char*)SB(b, h) + lds_byte(wc * 32 + n * 16 + fr, k * 32 + fq * 8))
; #define MMA(ai, bj, At, Bt_) do { __builtin_amdgcn_s_setprio(1); \
;     for (int m = 0; m < 4; ++m) for (int n = 0; n < 2; ++n) for (int k = 0; k < 2; ++k) \
;       acc[ai][bj][m][n] = __builtin_amdgcn_mfma_f32_16x16x32_bf16(At[m][k], Bt_[n][k], acc[ai][bj][m][n], 0, 0, 0); \
;     __builtin_amdgcn_s_setprio(0); } while (0)
; #define WAIT_V(n) asm volatile("s_waitcnt vmcnt(" #n ")" ::: "memory")
; #define WAIT_L(n) asm volatile("s_waitcnt lgkmcnt(" #n ")" ::: "memory")
; #define BAR __builtin_amdgcn_s_barrier()
;     ...
;       LDB(B1, 1, 1); WAIT_V(0); BAR; WAIT_L(0); MMA(0, 1, At, B1); BAR;
;       LDA(At, 1, 1); BAR; WAIT_L(0); MMA(1, 0, At, B0); MMA(1, 1, At, B1); BAR; }
;     if (wr == 0) BAR;
	ds_read_b128 v[140:143], v146
	ds_read_b128 v[236:239], v146 offset:1024
	ds_read_b128 v[240:243], v146 offset:2048
	ds_read_b128 v[144:147], v146 offset:3072
	s_waitcnt vmcnt(0)
	s_barrier
	s_waitcnt lgkmcnt(0)
	s_setprio 1
	s_waitcnt lgkmcnt(0)
	v_mfma_f32_16x16x32_bf16 v[98:101], v[2:5], v[140:143], v[224:227]
	v_mfma_f32_16x16x32_bf16 v[2:5], v[2:5], v[240:243], v[90:93]
	v_mfma_f32_16x16x32_bf16 v[118:121], v[6:9], v[144:147], v[2:5]
	v_mfma_f32_16x16x32_bf16 v[2:5], v[10:13], v[140:143], v[86:89]
	v_mfma_f32_16x16x32_bf16 v[102:105], v[18:21], v[236:239], v[2:5]
	v_mfma_f32_16x16x32_bf16 v[2:5], v[10:13], v[240:243], v[164:167]
	v_mfma_f32_16x16x32_bf16 v[122:125], v[18:21], v[144:147], v[2:5]
	v_mfma_f32_16x16x32_bf16 v[2:5], v[22:25], v[140:143], v[184:187]
	v_mfma_f32_16x16x32_bf16 v[90:93], v[26:29], v[236:239], v[2:5]
	v_mfma_f32_16x16x32_bf16 v[2:5], v[22:25], v[240:243], v[188:191]
	v_mfma_f32_16x16x32_bf16 v[110:113], v[26:29], v[144:147], v[2:5]
	v_mfma_f32_16x16x32_bf16 v[2:5], v[220:223], v[140:143], v[192:195]
	v_mfma_f32_16x16x32_bf16 v[86:89], v[232:235], v[236:239], v[2:5]
	v_mfma_f32_16x16x32_bf16 v[2:5], v[220:223], v[240:243], v[196:199]
	v_mfma_f32_16x16x32_bf16 v[98:101], v[6:9], v[236:239], v[98:101]
	v_mfma_f32_16x16x32_bf16 v[106:109], v[232:235], v[144:147], v[2:5]
	s_setprio 0
	s_barrier
	ds_read_b128 v[164:167], v133 offset:49152
	ds_read_b128 v[184:187], v133 offset:50176
	ds_read_b128 v[188:191], v134 offset:49152
	ds_read_b128 v[192:195], v134 offset:50176
	ds_read_b128 v[196:199], v137 offset:49152
	ds_read_b128 v[220:223], v137 offset:50176
	ds_read_b128 v[224:227], v139 offset:49152
	ds_read_b128 v[232:235], v139 offset:50176
	s_barrier
	s_waitcnt lgkmcnt(0)
	s_setprio 1
	s_waitcnt lgkmcnt(0)
	v_mfma_f32_16x16x32_bf16 v[6:9], v[164:167], v[204:207], v[58:61]
	v_mfma_f32_16x16x32_bf16 v[10:13], v[188:191], v[204:207], v[50:53]
	v_mfma_f32_16x16x32_bf16 v[2:5], v[164:167], v[14:17], v[62:65]
	v_mfma_f32_16x16x32_bf16 v[18:21], v[184:187], v[216:219], v[6:9]
	v_mfma_f32_16x16x32_bf16 v[6:9], v[188:191], v[14:17], v[54:57]
	v_mfma_f32_16x16x32_bf16 v[22:25], v[192:195], v[216:219], v[10:13]
	v_mfma_f32_16x16x32_bf16 v[10:13], v[196:199], v[14:17], v[46:49]
	v_mfma_f32_16x16x32_bf16 v[14:17], v[224:227], v[14:17], v[38:41]
	v_mfma_f32_16x16x32_bf16 v[2:5], v[184:187], v[30:33], v[2:5]
	v_mfma_f32_16x16x32_bf16 v[6:9], v[192:195], v[30:33], v[6:9]
	v_mfma_f32_16x16x32_bf16 v[10:13], v[220:223], v[30:33], v[10:13]
	v_mfma_f32_16x16x32_bf16 v[26:29], v[196:199], v[204:207], v[42:45]
	v_mfma_f32_16x16x32_bf16 v[14:17], v[232:235], v[30:33], v[14:17]
	v_mfma_f32_16x16x32_bf16 v[30:33], v[224:227], v[204:207], v[34:37]
	v_mfma_f32_16x16x32_bf16 v[26:29], v[220:223], v[216:219], v[26:29]
	v_mfma_f32_16x16x32_bf16 v[30:33], v[232:235], v[216:219], v[30:33]
	s_setprio 0
	s_setprio 1
	v_mfma_f32_16x16x32_bf16 v[38:41], v[164:167], v[240:243], v[152:155]
	v_mfma_f32_16x16x32_bf16 v[42:45], v[188:191], v[240:243], v[160:163]
	v_mfma_f32_16x16x32_bf16 v[46:49], v[196:199], v[240:243], v[228:231]
	v_mfma_f32_16x16x32_bf16 v[34:37], v[164:167], v[140:143], v[148:151]
	v_mfma_f32_16x16x32_bf16 v[50:53], v[184:187], v[144:147], v[38:41]
	v_mfma_f32_16x16x32_bf16 v[38:41], v[188:191], v[140:143], v[156:159]
	v_mfma_f32_16x16x32_bf16 v[54:57], v[192:195], v[144:147], v[42:45]
	v_mfma_f32_16x16x32_bf16 v[42:45], v[196:199], v[140:143], v[208:211]
	v_mfma_f32_16x16x32_bf16 v[58:61], v[220:223], v[144:147], v[46:49]
	v_mfma_f32_16x16x32_bf16 v[46:49], v[224:227], v[140:143], v[212:215]
	v_mfma_f32_16x16x32_bf16 v[62:65], v[224:227], v[240:243], v[200:203]
	v_mfma_f32_16x16x32_bf16 v[34:37], v[184:187], v[236:239], v[34:37]
	v_mfma_f32_16x16x32_bf16 v[38:41], v[192:195], v[236:239], v[38:41]
	v_mfma_f32_16x16x32_bf16 v[42:45], v[220:223], v[236:239], v[42:45]
	v_mfma_f32_16x16x32_bf16 v[46:49], v[232:235], v[236:239], v[46:49]
	v_mfma_f32_16x16x32_bf16 v[62:65], v[232:235], v[144:147], v[62:65]
	s_setprio 0
	v_readlane_b32 s4, v245, 33
	v_readlane_b32 s5, v245, 34
	s_and_b64 vcc, exec, s[4:5]
	s_barrier
	s_cbranch_vccz .LBB0_421
	s_barrier
